# DQK=64: eliminated per-tile P1 register copies (alternating P1 register sets between loop halves); GQA: C operand read directly from persistent negm regs; trimmed row-max canonicalization
# speedup vs baseline: 1.0274x; 1.0007x over previous
; __device__ __forceinline__ void finishSM(f32x16& p0, f32x16& p1, float alpha, float& l_reg, bf16x8& pa0, bf16x8& pa1, bf16x8& pa2, bf16x8& pa3) {
; #pragma unroll
;   for (int r = 0; r < 16; ++r) p1[r] = __builtin_amdgcn_exp2f(p1[r]);
;   float ps = 0;
; #pragma unroll
;   for (int r = 0; r < 16; ++r) ps += p0[r];
; #pragma unroll
;   for (int r = 0; r < 16; ++r) ps += p1[r];
;   { auto rr = __builtin_amdgcn_permlane32_swap(__float_as_uint(ps), __float_as_uint(ps), false, false);
;     ps = __uint_as_float(rr[0]) + __uint_as_float(rr[1]); }
;   l_reg = l_reg * alpha + ps;
;     ...
;   PK4(p0, 0, pa0); PK4(p0, 8, pa1); PK4(p1, 0, pa2); PK4(p1, 8, pa3);
;     ...
; }
; template <int DQK> __device__ __forceinline__ void qkt(f32x16& p0, f32x16& p1, const char* Ks, const bf16x8* qr, int r32, int hi, const f32x16& negm) {
; #pragma unroll
;   for (int d0 = 0; d0 < DQK / 16; ++d0) { const int cb = (d0 * 16 + hi * 8) * 2;
;     const bf16x8 b0 = *reinterpret_cast<const bf16x8*>(Ks + (DQK == 128 ? KSWZ(r32, cb) : KSWZ64(r32, cb)));
;     const bf16x8 b1 = *reinterpret_cast<const bf16x8*>(Ks + (DQK == 128 ? KSWZ(32 + r32, cb) : KSWZ64(32 + r32, cb)));
;     if (d0 == 0) { p0 = __builtin_amdgcn_mfma_f32_32x32x16_bf16(b0, qr[0], negm, 0, 0, 0); p1 = __builtin_amdgcn_mfma_f32_32x32x16_bf16(b1, qr[0], negm, 0, 0, 0); }
;     else { p0 = __builtin_amdgcn_mfma_f32_32x32x16_bf16(b0, qr[d0], p0, 0, 0, 0); p1 = __builtin_amdgcn_mfma_f32_32x32x16_bf16(b1, qr[d0], p1, 0, 0, 0); } }
; }
.LBB0_69:
	s_add_i32 s99, s12, 64
	s_cmp_le_u32 s99, s16
	s_cbranch_scc0 .Lslow_g1
	ds_read_b128 v[198:201], v195 offset:57344
	ds_read_b128 v[202:205], v195 offset:49152
	ds_read_b128 v[244:247], v211 offset:57344
	ds_read_b128 v[206:209], v211 offset:49152
	v_add_f32_e32 v227, 0, v238
	v_add_f32_e32 v227, v240, v227
	v_cvt_pk_bf16_f32 v66, v238, v240
	v_add_f32_e32 v227, v236, v227
	v_add_f32_e32 v227, v239, v227
	v_cvt_pk_bf16_f32 v67, v236, v239
	v_add_f32_e32 v227, v235, v227
	v_add_f32_e32 v227, v237, v227
	v_cvt_pk_bf16_f32 v68, v235, v237
	v_add_f32_e32 v227, v233, v227
	v_add_f32_e32 v227, v234, v227
	v_cvt_pk_bf16_f32 v69, v233, v234
	s_waitcnt lgkmcnt(3)
	v_mfma_f32_32x32x16_bf16 v[114:129], v[198:201], v[174:177], v[82:97]
	v_add_f32_e32 v227, v184, v227
	v_add_f32_e32 v227, v232, v227
	v_cvt_pk_bf16_f32 v70, v184, v232
	v_add_f32_e32 v227, v183, v227
	v_add_f32_e32 v227, v185, v227
	s_waitcnt lgkmcnt(2)
	v_mfma_f32_32x32x16_bf16 v[130:145], v[202:205], v[174:177], v[82:97]
	ds_read_b128 v[198:201], v210 offset:57344
	ds_read_b128 v[202:205], v210 offset:49152
	v_cvt_pk_bf16_f32 v71, v183, v185
	v_add_f32_e32 v227, v180, v227
	v_add_f32_e32 v227, v182, v227
	v_cvt_pk_bf16_f32 v72, v180, v182
	v_add_f32_e32 v227, v179, v227
	s_waitcnt lgkmcnt(3)
	v_mfma_f32_32x32x16_bf16 v[114:129], v[244:247], v[170:173], v[114:129]
	v_add_f32_e32 v227, v181, v227
	v_cvt_pk_bf16_f32 v73, v179, v181
	v_exp_f32_e32 v98, v98
	v_exp_f32_e32 v99, v99
	v_permlane32_swap_b32_e32 v66, v68
	s_waitcnt lgkmcnt(2)
	v_mfma_f32_32x32x16_bf16 v[130:145], v[206:209], v[170:173], v[130:145]
	ds_read_b128 v[244:247], v197 offset:57344
	ds_read_b128 v[206:209], v197 offset:49152
	v_permlane32_swap_b32_e32 v67, v69
	v_permlane32_swap_b32_e32 v70, v72
	v_permlane32_swap_b32_e32 v71, v73
	v_exp_f32_e32 v100, v100
	v_add_f32_e32 v227, v98, v227
	s_waitcnt lgkmcnt(3)
	v_mfma_f32_32x32x16_bf16 v[114:129], v[198:201], v[166:169], v[114:129]
	v_exp_f32_e32 v101, v101
	v_add_f32_e32 v227, v99, v227
	v_exp_f32_e32 v102, v102
	v_add_f32_e32 v227, v100, v227
	v_exp_f32_e32 v103, v103
	s_waitcnt lgkmcnt(2)
	v_mfma_f32_32x32x16_bf16 v[130:145], v[202:205], v[166:169], v[130:145]
	ds_read_b128 v[198:201], v196 offset:57344
	ds_read_b128 v[202:205], v196 offset:49152
	v_add_f32_e32 v227, v101, v227
	v_exp_f32_e32 v104, v104
	v_add_f32_e32 v227, v102, v227
	v_exp_f32_e32 v105, v105
	s_waitcnt lgkmcnt(3)
	v_mfma_f32_32x32x16_bf16 v[114:129], v[244:247], v[162:165], v[114:129]
	v_add_f32_e32 v227, v103, v227
	v_exp_f32_e32 v106, v106
	v_add_f32_e32 v227, v104, v227
	v_exp_f32_e32 v107, v107
	s_waitcnt lgkmcnt(2)
	v_mfma_f32_32x32x16_bf16 v[130:145], v[206:209], v[162:165], v[130:145]
	ds_read_b128 v[244:247], v222 offset:57344
	ds_read_b128 v[206:209], v222 offset:49152
	v_add_f32_e32 v227, v105, v227
	v_exp_f32_e32 v108, v108
	v_add_f32_e32 v227, v106, v227
	v_exp_f32_e32 v109, v109
	s_waitcnt lgkmcnt(3)
	v_mfma_f32_32x32x16_bf16 v[114:129], v[198:201], v[158:161], v[114:129]
	v_add_f32_e32 v227, v107, v227
	v_exp_f32_e32 v110, v110
	v_add_f32_e32 v227, v108, v227
	v_exp_f32_e32 v111, v111
	s_waitcnt lgkmcnt(2)
	v_mfma_f32_32x32x16_bf16 v[130:145], v[202:205], v[158:161], v[130:145]
	ds_read_b128 v[198:201], v223 offset:57344
	ds_read_b128 v[202:205], v223 offset:49152
	v_add_f32_e32 v227, v109, v227
	v_exp_f32_e32 v112, v112
	v_add_f32_e32 v227, v110, v227
	v_exp_f32_e32 v113, v113
	s_waitcnt lgkmcnt(3)
	v_mfma_f32_32x32x16_bf16 v[114:129], v[244:247], v[154:157], v[114:129]
	v_add_f32_e32 v227, v111, v227
	v_add_f32_e32 v227, v112, v227
	v_add_f32_e32 v227, v113, v227
	v_mov_b32_e32 v228, v227
	s_waitcnt lgkmcnt(2)
	v_mfma_f32_32x32x16_bf16 v[130:145], v[206:209], v[154:157], v[130:145]
	ds_read_b128 v[244:247], v224 offset:57344
	ds_read_b128 v[206:209], v224 offset:49152
	v_cvt_pk_bf16_f32 v74, v98, v99
	v_cvt_pk_bf16_f32 v75, v100, v101
	v_cvt_pk_bf16_f32 v76, v102, v103
	v_cvt_pk_bf16_f32 v77, v104, v105
	s_waitcnt lgkmcnt(3)
	v_mfma_f32_32x32x16_bf16 v[114:129], v[198:201], v[150:153], v[114:129]
	v_cvt_pk_bf16_f32 v78, v106, v107
	v_cvt_pk_bf16_f32 v79, v108, v109
	v_cvt_pk_bf16_f32 v80, v110, v111
	v_cvt_pk_bf16_f32 v81, v112, v113
	s_waitcnt lgkmcnt(2)
; #define SBAR() __builtin_amdgcn_sched_barrier(0)
; template <bool FIRST> __device__ __forceinline__ void partialSM(f32x16& p0, f32x16& p1, float& m_reg, float& alpha, f32x16& negm, float c_cur) {
;   float pmax = p0[0];
; #pragma unroll
;   for (int r = 1; r < 16; ++r) pmax = fmaxf(pmax, p0[r]);
; #pragma unroll
;   for (int r = 0; r < 16; ++r) pmax = fmaxf(pmax, p1[r]);
;   { auto rr = __builtin_amdgcn_permlane32_swap(__float_as_uint(pmax), __float_as_uint(pmax), false, false);
;     pmax = fmaxf(__uint_as_float(rr[0]), __uint_as_float(rr[1])); }
; template <int D0> __device__ __forceinline__ void pv_one(f32x16& od, int vb, bf16x8 pa0, bf16x8 pa1, bf16x8 pa2, bf16x8 pa3) {
;   const s16x4 l0 = tr_read<v_rd_off(D0, 0, 0)>(vb), h0 = tr_read<v_rd_off(D0, 0, 1)>(vb), l1 = tr_read<v_rd_off(D0, 1, 0)>(vb), h1 = tr_read<v_rd_off(D0, 1, 1)>(vb);
;   const s16x4 l2 = tr_read<v_rd_off(D0, 2, 0)>(vb), h2 = tr_read<v_rd_off(D0, 2, 1)>(vb), l3 = tr_read<v_rd_off(D0, 3, 0)>(vb), h3 = tr_read<v_rd_off(D0, 3, 1)>(vb);
;   asm volatile("s_waitcnt lgkmcnt(0)" ::: "memory"); SBAR();
;     ...
;   od = __builtin_amdgcn_mfma_f32_32x32x16_bf16(pa0, PK(l0, h0), od, 0, 0, 0);
;   od = __builtin_amdgcn_mfma_f32_32x32x16_bf16(pa1, PK(l1, h1), od, 0, 0, 0);
;   od = __builtin_amdgcn_mfma_f32_32x32x16_bf16(pa2, PK(l2, h2), od, 0, 0, 0);
;   od = __builtin_amdgcn_mfma_f32_32x32x16_bf16(pa3, PK(l3, h3), od, 0, 0, 0);
;     ...
; }
; __device__ __forceinline__ void pv_d0(f32x16* o, int vb, bf16x8 pa0, bf16x8 pa1, bf16x8 pa2, bf16x8 pa3) {
;   pv_one<0>(o[0], vb, pa0, pa1, pa2, pa3); pv_one<1>(o[1], vb, pa0, pa1, pa2, pa3); pv_one<2>(o[2], vb, pa0, pa1, pa2, pa3); pv_one<3>(o[3], vb, pa0, pa1, pa2, pa3);
	v_mfma_f32_32x32x16_bf16 v[130:145], v[202:205], v[150:153], v[130:145]
	ds_read_b64_tr_b16 v[178:179], v193 offset:0
	ds_read_b64_tr_b16 v[180:181], v193 offset:0x800
	ds_read_b64_tr_b16 v[182:183], v193 offset:0x200
	ds_read_b64_tr_b16 v[184:185], v193 offset:0xa00
	ds_read_b64_tr_b16 v[198:199], v193 offset:0x400
	ds_read_b64_tr_b16 v[200:201], v193 offset:0xc00
	ds_read_b64_tr_b16 v[202:203], v193 offset:0x600
	ds_read_b64_tr_b16 v[204:205], v193 offset:0xe00
	v_permlane32_swap_b32_e32 v227, v228
	v_permlane32_swap_b32_e32 v74, v76
	v_permlane32_swap_b32_e32 v75, v77
	v_permlane32_swap_b32_e32 v78, v80
	s_waitcnt lgkmcnt(9)
	v_mfma_f32_32x32x16_bf16 v[114:129], v[244:247], v[146:149], v[114:129]
	v_permlane32_swap_b32_e32 v79, v81
	v_add_co_u32_e32 v218, vcc, s77, v186
	s_nop 1
	v_addc_co_u32_e32 v219, vcc, 0, v187, vcc
	s_waitcnt lgkmcnt(8)
	v_mfma_f32_32x32x16_bf16 v[130:145], v[206:209], v[146:149], v[130:145]
	global_load_dwordx4 v[98:101], v[186:187], off offset:512
	global_load_dwordx4 v[102:105], v[186:187], off
	global_load_dwordx4 v[110:113], v[218:219], off offset:512
	global_load_dwordx4 v[106:109], v[218:219], off
	s_waitcnt lgkmcnt(6)
	v_mfma_f32_32x32x16_bf16 v[2:17], v[66:69], v[178:181], v[2:17]
	ds_read_b64_tr_b16 v[178:179], v193 offset:0x1000
	ds_read_b64_tr_b16 v[180:181], v193 offset:0x1800
	s_waitcnt lgkmcnt(6)
	v_mfma_f32_32x32x16_bf16 v[50:65], v[66:69], v[182:185], v[50:65]
	ds_read_b64_tr_b16 v[182:183], v193 offset:0x1200
	ds_read_b64_tr_b16 v[184:185], v193 offset:0x1a00
	s_waitcnt lgkmcnt(6)
	v_mfma_f32_32x32x16_bf16 v[34:49], v[66:69], v[198:201], v[34:49]
	ds_read_b64_tr_b16 v[198:199], v193 offset:0x1400
	ds_read_b64_tr_b16 v[200:201], v193 offset:0x1c00
	s_waitcnt lgkmcnt(6)
	v_mfma_f32_32x32x16_bf16 v[18:33], v[66:69], v[202:205], v[18:33]
	ds_read_b64_tr_b16 v[202:203], v193 offset:0x1600
	ds_read_b64_tr_b16 v[204:205], v193 offset:0x1e00
	s_waitcnt lgkmcnt(6)
	v_mfma_f32_32x32x16_bf16 v[2:17], v[70:73], v[178:181], v[2:17]
	ds_read_b64_tr_b16 v[178:179], v193 offset:0x2000
	ds_read_b64_tr_b16 v[180:181], v193 offset:0x2800
	v_max_f32_e32 v218, v130, v131
	v_max3_f32 v218, v218, v132, v133
	s_waitcnt lgkmcnt(6)
	v_mfma_f32_32x32x16_bf16 v[50:65], v[70:73], v[182:185], v[50:65]
	ds_read_b64_tr_b16 v[182:183], v193 offset:0x2200
	ds_read_b64_tr_b16 v[184:185], v193 offset:0x2a00
	v_max3_f32 v218, v218, v134, v135
	v_max3_f32 v218, v218, v136, v137
	s_waitcnt lgkmcnt(6)
	v_mfma_f32_32x32x16_bf16 v[34:49], v[70:73], v[198:201], v[34:49]
	ds_read_b64_tr_b16 v[198:199], v193 offset:0x2400
	ds_read_b64_tr_b16 v[200:201], v193 offset:0x2c00
	v_max3_f32 v218, v218, v138, v139
	v_max3_f32 v218, v218, v140, v141
	s_waitcnt lgkmcnt(6)
	v_mfma_f32_32x32x16_bf16 v[18:33], v[70:73], v[202:205], v[18:33]
	ds_read_b64_tr_b16 v[202:203], v193 offset:0x2600
	ds_read_b64_tr_b16 v[204:205], v193 offset:0x2e00
	v_max3_f32 v218, v218, v142, v143
	v_max3_f32 v218, v218, v144, v145
	s_waitcnt lgkmcnt(6)
	v_mfma_f32_32x32x16_bf16 v[2:17], v[74:77], v[178:181], v[2:17]
	ds_read_b64_tr_b16 v[178:179], v193 offset:0x3000
	ds_read_b64_tr_b16 v[180:181], v193 offset:0x3800
	v_max3_f32 v218, v218, v114, v115
	v_max3_f32 v218, v218, v116, v117
	s_waitcnt lgkmcnt(6)
	v_mfma_f32_32x32x16_bf16 v[50:65], v[74:77], v[182:185], v[50:65]
	ds_read_b64_tr_b16 v[182:183], v193 offset:0x3200
	ds_read_b64_tr_b16 v[184:185], v193 offset:0x3a00
	v_max3_f32 v218, v218, v118, v119
	v_max3_f32 v218, v218, v120, v121
	s_waitcnt lgkmcnt(6)
	v_mfma_f32_32x32x16_bf16 v[34:49], v[74:77], v[198:201], v[34:49]
	ds_read_b64_tr_b16 v[198:199], v193 offset:0x3400
	ds_read_b64_tr_b16 v[200:201], v193 offset:0x3c00
	v_max3_f32 v218, v218, v122, v123
	s_waitcnt lgkmcnt(6)
	v_mfma_f32_32x32x16_bf16 v[18:33], v[74:77], v[202:205], v[18:33]
	ds_read_b64_tr_b16 v[202:203], v193 offset:0x3600
	ds_read_b64_tr_b16 v[204:205], v193 offset:0x3e00
	v_max3_f32 v218, v218, v124, v125
	s_waitcnt lgkmcnt(6)
	v_mfma_f32_32x32x16_bf16 v[2:17], v[78:81], v[178:181], v[2:17]
	v_max3_f32 v218, v218, v126, v127
	s_waitcnt lgkmcnt(4)
	v_mfma_f32_32x32x16_bf16 v[50:65], v[78:81], v[182:185], v[50:65]
	v_max3_f32 v218, v218, v128, v129
	s_waitcnt lgkmcnt(2)
	v_mfma_f32_32x32x16_bf16 v[34:49], v[78:81], v[198:201], v[34:49]
	v_mov_b32_e32 v219, v218
	s_waitcnt lgkmcnt(0)
	v_mfma_f32_32x32x16_bf16 v[18:33], v[78:81], v[202:205], v[18:33]
	v_permlane32_swap_b32_e32 v218, v219
	v_max_f32_e32 v66, v218, v219
	s_branch .Ljoin_g1

; template <bool FIRST> __device__ __forceinline__ void partialSM(f32x16& p0, f32x16& p1, float& m_reg, float& alpha, f32x16& negm, float c_cur) {
;     ...
;   alpha = 1.f;
;   if (FIRST || !__builtin_expect(__all(pmax <= THR2), 1)) {
;     const float d = FIRST ? pmax : fmaxf(pmax, 0.f); m_reg += d; if (!FIRST) alpha = __builtin_amdgcn_exp2f(-d);
.Ljoin_g1:
	v_cmp_ge_f32_e32 vcc, s30, v66
	s_cmp_eq_u64 vcc, exec
	s_cbranch_scc0 .LBB0_87
	v_mov_b32_e32 v229, 1.0

; #define SBAR() __builtin_amdgcn_sched_barrier(0)
; #define SWAIT() do { if (SDEPTH == 1) asm volatile("s_waitcnt vmcnt(0)" ::: "memory"); else if (DQK == 128) asm volatile("s_waitcnt vmcnt(4)" ::: "memory"); else asm volatile("s_waitcnt vmcnt(3)" ::: "memory"); } while (0)
; __device__ __forceinline__ void finishSM(f32x16& p0, f32x16& p1, float alpha, float& l_reg, bf16x8& pa0, bf16x8& pa1, bf16x8& pa2, bf16x8& pa3) {
; #pragma unroll
;   for (int r = 0; r < 16; ++r) p1[r] = __builtin_amdgcn_exp2f(p1[r]);
;   float ps = 0;
; #pragma unroll
;   for (int r = 0; r < 16; ++r) ps += p0[r];
; #pragma unroll
;   for (int r = 0; r < 16; ++r) ps += p1[r];
;   { auto rr = __builtin_amdgcn_permlane32_swap(__float_as_uint(ps), __float_as_uint(ps), false, false);
;     ps = __uint_as_float(rr[0]) + __uint_as_float(rr[1]); }
;   l_reg = l_reg * alpha + ps;
;     ...
;   PK4(p0, 0, pa0); PK4(p0, 8, pa1); PK4(p1, 0, pa2); PK4(p1, 8, pa3);
;     ...
; }
; template <int DQK> __device__ __forceinline__ void qkt(f32x16& p0, f32x16& p1, const char* Ks, const bf16x8* qr, int r32, int hi, const f32x16& negm) {
; #pragma unroll
;   for (int d0 = 0; d0 < DQK / 16; ++d0) { const int cb = (d0 * 16 + hi * 8) * 2;
;     const bf16x8 b0 = *reinterpret_cast<const bf16x8*>(Ks + (DQK == 128 ? KSWZ(r32, cb) : KSWZ64(r32, cb)));
;     const bf16x8 b1 = *reinterpret_cast<const bf16x8*>(Ks + (DQK == 128 ? KSWZ(32 + r32, cb) : KSWZ64(32 + r32, cb)));
;     if (d0 == 0) { p0 = __builtin_amdgcn_mfma_f32_32x32x16_bf16(b0, qr[0], negm, 0, 0, 0); p1 = __builtin_amdgcn_mfma_f32_32x32x16_bf16(b1, qr[0], negm, 0, 0, 0); }
;     else { p0 = __builtin_amdgcn_mfma_f32_32x32x16_bf16(b0, qr[d0], p0, 0, 0, 0); p1 = __builtin_amdgcn_mfma_f32_32x32x16_bf16(b1, qr[d0], p1, 0, 0, 0); } }
; }
; template <int DQK, bool BIAS, bool VIRT = false>
; __device__ __forceinline__ void attn_pass(const bf16_t* __restrict__ Qb, const bf16_t* __restrict__ Kh, const bf16_t* __restrict__ Vh, int L, int NT, int qw0, const float* lut, f32x16 (&o)[4], char* lds, int nact) {
;     ...
;     __syncthreads(); SWAIT(); SWRITE(0, SE);
;     RESC(alB); __syncthreads();
;     NEGM(j + 1); SBAR(); qkt<DQK>(pA0, pA1, K_lds, qr, r32, hi, negm);
;     finishSM(pB0, pB1, alB, l_reg, pa0, pa1, pa2, pa3); SBAR();
;     if (SDEPTH == 1 || j + 3 < NT) SLOAD(SE, (j + 1 + SDEPTH) * KVBLK); SBAR();
.LBB0_76:
	s_add_i32 s14, s12, 0x80
	v_exp_f32_e32 v178, v130
	v_exp_f32_e32 v205, v131
	v_exp_f32_e32 v179, v132
	v_exp_f32_e32 v204, v133
	v_exp_f32_e32 v180, v134
	v_exp_f32_e32 v203, v135
	v_exp_f32_e32 v181, v136
	v_exp_f32_e32 v202, v137
	v_exp_f32_e32 v182, v138
	v_exp_f32_e32 v201, v139
	v_exp_f32_e32 v183, v140
	v_exp_f32_e32 v200, v141
	v_exp_f32_e32 v184, v142
	v_exp_f32_e32 v199, v143
	v_exp_f32_e32 v185, v144
	v_exp_f32_e32 v198, v145
	s_waitcnt lgkmcnt(0)
	s_barrier
	s_cmp_le_u32 s14, s16
	s_cbranch_scc0 .Lslow_g2
	ds_read_b128 v[232:235], v195 offset:40960
	ds_read_b128 v[236:239], v195 offset:32768
	ds_read_b128 v[244:247], v211 offset:40960
	ds_read_b128 v[240:243], v211 offset:32768
	v_add_f32_e32 v230, 0, v178
	v_add_f32_e32 v230, v205, v230
	v_cvt_pk_bf16_f32 v178, v178, v205
	v_add_f32_e32 v230, v179, v230
	v_add_f32_e32 v230, v204, v230
	v_cvt_pk_bf16_f32 v179, v179, v204
	v_add_f32_e32 v230, v180, v230
	v_add_f32_e32 v230, v203, v230
	v_cvt_pk_bf16_f32 v180, v180, v203
	v_add_f32_e32 v230, v181, v230
	v_add_f32_e32 v230, v202, v230
	v_cvt_pk_bf16_f32 v181, v181, v202
	s_waitcnt lgkmcnt(3)
	v_mfma_f32_32x32x16_bf16 v[98:113], v[232:235], v[174:177], v[82:97]
	v_add_f32_e32 v230, v182, v230
	v_add_f32_e32 v230, v201, v230
	v_cvt_pk_bf16_f32 v182, v182, v201
	v_add_f32_e32 v230, v183, v230
	v_add_f32_e32 v230, v200, v230
	s_waitcnt lgkmcnt(2)
	v_mfma_f32_32x32x16_bf16 v[130:145], v[236:239], v[174:177], v[82:97]
	ds_read_b128 v[232:235], v210 offset:40960
	ds_read_b128 v[236:239], v210 offset:32768
	v_cvt_pk_bf16_f32 v183, v183, v200
	v_add_f32_e32 v230, v184, v230
	v_add_f32_e32 v230, v199, v230
	v_cvt_pk_bf16_f32 v184, v184, v199
	v_add_f32_e32 v230, v185, v230
	s_waitcnt lgkmcnt(3)
	v_mfma_f32_32x32x16_bf16 v[98:113], v[244:247], v[170:173], v[98:113]
	v_add_f32_e32 v230, v198, v230
	v_cvt_pk_bf16_f32 v185, v185, v198
	v_exp_f32_e32 v114, v114
	v_exp_f32_e32 v115, v115
	v_permlane32_swap_b32_e32 v178, v180
	s_waitcnt lgkmcnt(2)
	v_mfma_f32_32x32x16_bf16 v[130:145], v[240:243], v[170:173], v[130:145]
	ds_read_b128 v[244:247], v197 offset:40960
	ds_read_b128 v[240:243], v197 offset:32768
	v_permlane32_swap_b32_e32 v179, v181
	v_permlane32_swap_b32_e32 v182, v184
	v_permlane32_swap_b32_e32 v183, v185
	v_exp_f32_e32 v116, v116
	v_add_f32_e32 v230, v114, v230
	s_waitcnt lgkmcnt(3)
	v_mfma_f32_32x32x16_bf16 v[98:113], v[232:235], v[166:169], v[98:113]
	v_exp_f32_e32 v117, v117
	v_add_f32_e32 v230, v115, v230
	v_exp_f32_e32 v118, v118
	v_add_f32_e32 v230, v116, v230
	v_exp_f32_e32 v119, v119
	s_waitcnt lgkmcnt(2)
	v_mfma_f32_32x32x16_bf16 v[130:145], v[236:239], v[166:169], v[130:145]
	ds_read_b128 v[232:235], v196 offset:40960
	ds_read_b128 v[236:239], v196 offset:32768
	v_add_f32_e32 v230, v117, v230
	v_exp_f32_e32 v120, v120
	v_add_f32_e32 v230, v118, v230
	v_exp_f32_e32 v121, v121
	s_waitcnt lgkmcnt(3)
	v_mfma_f32_32x32x16_bf16 v[98:113], v[244:247], v[162:165], v[98:113]
	v_add_f32_e32 v230, v119, v230
	v_exp_f32_e32 v122, v122
	v_add_f32_e32 v230, v120, v230
	v_exp_f32_e32 v123, v123
	s_waitcnt lgkmcnt(2)
	v_mfma_f32_32x32x16_bf16 v[130:145], v[240:243], v[162:165], v[130:145]
	ds_read_b128 v[244:247], v222 offset:40960
	ds_read_b128 v[240:243], v222 offset:32768
	v_add_f32_e32 v230, v121, v230
	v_exp_f32_e32 v124, v124
	v_add_f32_e32 v230, v122, v230
	v_exp_f32_e32 v125, v125
	s_waitcnt lgkmcnt(3)
	v_mfma_f32_32x32x16_bf16 v[98:113], v[232:235], v[158:161], v[98:113]
	v_add_f32_e32 v230, v123, v230
	v_exp_f32_e32 v126, v126
	v_add_f32_e32 v230, v124, v230
	v_exp_f32_e32 v127, v127
	s_waitcnt lgkmcnt(2)
	v_mfma_f32_32x32x16_bf16 v[130:145], v[236:239], v[158:161], v[130:145]
	ds_read_b128 v[232:235], v223 offset:40960
	ds_read_b128 v[236:239], v223 offset:32768
	v_add_f32_e32 v230, v125, v230
	v_exp_f32_e32 v128, v128
	v_add_f32_e32 v230, v126, v230
	v_exp_f32_e32 v129, v129
	s_waitcnt lgkmcnt(3)
	v_mfma_f32_32x32x16_bf16 v[98:113], v[244:247], v[154:157], v[98:113]
	v_add_f32_e32 v230, v127, v230
	v_add_f32_e32 v230, v128, v230
	v_add_f32_e32 v230, v129, v230
	v_mov_b32_e32 v231, v230
	s_waitcnt lgkmcnt(2)
	v_mfma_f32_32x32x16_bf16 v[130:145], v[240:243], v[154:157], v[130:145]
	ds_read_b128 v[244:247], v224 offset:40960
	ds_read_b128 v[240:243], v224 offset:32768
	v_cvt_pk_bf16_f32 v198, v114, v115
	v_cvt_pk_bf16_f32 v199, v116, v117
	v_cvt_pk_bf16_f32 v200, v118, v119
	v_cvt_pk_bf16_f32 v201, v120, v121
	s_waitcnt lgkmcnt(3)
	v_mfma_f32_32x32x16_bf16 v[98:113], v[232:235], v[150:153], v[98:113]
	v_cvt_pk_bf16_f32 v202, v122, v123
	v_cvt_pk_bf16_f32 v203, v124, v125
	v_cvt_pk_bf16_f32 v204, v126, v127
	v_cvt_pk_bf16_f32 v205, v128, v129
	s_waitcnt lgkmcnt(2)
	v_mfma_f32_32x32x16_bf16 v[130:145], v[236:239], v[150:153], v[130:145]
	ds_read_b64_tr_b16 v[206:207], v190 offset:0
	ds_read_b64_tr_b16 v[208:209], v190 offset:0x800
	ds_read_b64_tr_b16 v[232:233], v190 offset:0x200
	ds_read_b64_tr_b16 v[234:235], v190 offset:0xa00
	ds_read_b64_tr_b16 v[236:237], v190 offset:0x400
	ds_read_b64_tr_b16 v[238:239], v190 offset:0xc00
	v_permlane32_swap_b32_e32 v230, v231
	v_permlane32_swap_b32_e32 v198, v200
	v_permlane32_swap_b32_e32 v199, v201
	v_permlane32_swap_b32_e32 v202, v204
	s_waitcnt lgkmcnt(7)
	v_mfma_f32_32x32x16_bf16 v[98:113], v[244:247], v[146:149], v[98:113]
	v_permlane32_swap_b32_e32 v203, v205
	v_add_co_u32_e32 v218, vcc, s80, v186
	s_nop 1
	v_addc_co_u32_e32 v219, vcc, 0, v187, vcc
	s_waitcnt lgkmcnt(6)
	v_mfma_f32_32x32x16_bf16 v[130:145], v[240:243], v[146:149], v[130:145]
	ds_read_b64_tr_b16 v[240:241], v190 offset:0x600
	ds_read_b64_tr_b16 v[242:243], v190 offset:0xe00
	global_load_dwordx4 v[114:117], v[218:219], off offset:512
	global_load_dwordx4 v[118:121], v[218:219], off
	s_waitcnt lgkmcnt(6)
; #define SBAR() __builtin_amdgcn_sched_barrier(0)
; template <int DQK> __device__ __forceinline__ void qkt(f32x16& p0, f32x16& p1, const char* Ks, const bf16x8* qr, int r32, int hi, const f32x16& negm) {
; #pragma unroll
;   for (int d0 = 0; d0 < DQK / 16; ++d0) { const int cb = (d0 * 16 + hi * 8) * 2;
;     const bf16x8 b0 = *reinterpret_cast<const bf16x8*>(Ks + (DQK == 128 ? KSWZ(r32, cb) : KSWZ64(r32, cb)));
;     const bf16x8 b1 = *reinterpret_cast<const bf16x8*>(Ks + (DQK == 128 ? KSWZ(32 + r32, cb) : KSWZ64(32 + r32, cb)));
;     if (d0 == 0) { p0 = __builtin_amdgcn_mfma_f32_32x32x16_bf16(b0, qr[0], negm, 0, 0, 0); p1 = __builtin_amdgcn_mfma_f32_32x32x16_bf16(b1, qr[0], negm, 0, 0, 0); }
;     else { p0 = __builtin_amdgcn_mfma_f32_32x32x16_bf16(b0, qr[d0], p0, 0, 0, 0); p1 = __builtin_amdgcn_mfma_f32_32x32x16_bf16(b1, qr[d0], p1, 0, 0, 0); } }
; }
; __device__ __forceinline__ int v_st(int k, int c) { const int kk = (k & ~0xC) | ((k & 4) << 1) | ((k & 8) >> 1); return ((kk >> 3) * 4 + (c >> 5)) * 512 + ((kk & 7) * 32 + (c & 31)) * 2; }
; __device__ __forceinline__ int v_rd_base(int lane) { return ((lane & 3) << 3) | (((lane >> 2) & 3) << 6) | (((lane >> 4) & 1) << 5) | (((lane >> 5) & 1) << 8); }
; template <int OFF> __device__ __forceinline__ s16x4 tr_read(int vb) {
;   s16x4 r; asm volatile("ds_read_b64_tr_b16 %0, %1 offset:%2" : "=&v"(r) : "v"(vb), "i"(OFF) : "memory"); return r;
; }
; template <int D0> __device__ __forceinline__ void pv_one(f32x16& od, int vb, bf16x8 pa0, bf16x8 pa1, bf16x8 pa2, bf16x8 pa3) {
;   const s16x4 l0 = tr_read<v_rd_off(D0, 0, 0)>(vb), h0 = tr_read<v_rd_off(D0, 0, 1)>(vb), l1 = tr_read<v_rd_off(D0, 1, 0)>(vb), h1 = tr_read<v_rd_off(D0, 1, 1)>(vb);
;   const s16x4 l2 = tr_read<v_rd_off(D0, 2, 0)>(vb), h2 = tr_read<v_rd_off(D0, 2, 1)>(vb), l3 = tr_read<v_rd_off(D0, 3, 0)>(vb), h3 = tr_read<v_rd_off(D0, 3, 1)>(vb);
;   asm volatile("s_waitcnt lgkmcnt(0)" ::: "memory"); SBAR();
;     ...
;   od = __builtin_amdgcn_mfma_f32_32x32x16_bf16(pa0, PK(l0, h0), od, 0, 0, 0);
;   od = __builtin_amdgcn_mfma_f32_32x32x16_bf16(pa1, PK(l1, h1), od, 0, 0, 0);
;   od = __builtin_amdgcn_mfma_f32_32x32x16_bf16(pa2, PK(l2, h2), od, 0, 0, 0);
;   od = __builtin_amdgcn_mfma_f32_32x32x16_bf16(pa3, PK(l3, h3), od, 0, 0, 0);
;     ...
; }
; __device__ __forceinline__ void pv_d0(f32x16* o, int vb, bf16x8 pa0, bf16x8 pa1, bf16x8 pa2, bf16x8 pa3) {
	v_mfma_f32_32x32x16_bf16 v[2:17], v[178:181], v[206:209], v[2:17]
	ds_read_b64_tr_b16 v[206:207], v190 offset:0x1000
	ds_read_b64_tr_b16 v[208:209], v190 offset:0x1800
	v_add_co_u32_e32 v218, vcc, s81, v186
	s_nop 1
	v_addc_co_u32_e32 v219, vcc, 0, v187, vcc
	global_load_dwordx4 v[126:129], v[218:219], off offset:512
	global_load_dwordx4 v[122:125], v[218:219], off
	s_waitcnt lgkmcnt(6)
	v_mfma_f32_32x32x16_bf16 v[50:65], v[178:181], v[232:235], v[50:65]
	ds_read_b64_tr_b16 v[232:233], v190 offset:0x1200
	ds_read_b64_tr_b16 v[234:235], v190 offset:0x1a00
	s_waitcnt lgkmcnt(6)
	v_mfma_f32_32x32x16_bf16 v[34:49], v[178:181], v[236:239], v[34:49]
	ds_read_b64_tr_b16 v[236:237], v190 offset:0x1400
	ds_read_b64_tr_b16 v[238:239], v190 offset:0x1c00
	s_waitcnt lgkmcnt(6)
	v_mfma_f32_32x32x16_bf16 v[18:33], v[178:181], v[240:243], v[18:33]
	ds_read_b64_tr_b16 v[240:241], v190 offset:0x1600
	ds_read_b64_tr_b16 v[242:243], v190 offset:0x1e00
	s_waitcnt lgkmcnt(6)
	v_mfma_f32_32x32x16_bf16 v[2:17], v[182:185], v[206:209], v[2:17]
	ds_read_b64_tr_b16 v[206:207], v190 offset:0x2000
	ds_read_b64_tr_b16 v[208:209], v190 offset:0x2800
	v_max_f32_e32 v218, v130, v131
	v_max3_f32 v218, v218, v132, v133
	s_waitcnt lgkmcnt(6)
	v_mfma_f32_32x32x16_bf16 v[50:65], v[182:185], v[232:235], v[50:65]
	ds_read_b64_tr_b16 v[232:233], v190 offset:0x2200
	ds_read_b64_tr_b16 v[234:235], v190 offset:0x2a00
	v_max3_f32 v218, v218, v134, v135
	v_max3_f32 v218, v218, v136, v137
	s_waitcnt lgkmcnt(6)
	v_mfma_f32_32x32x16_bf16 v[34:49], v[182:185], v[236:239], v[34:49]
	ds_read_b64_tr_b16 v[236:237], v190 offset:0x2400
	ds_read_b64_tr_b16 v[238:239], v190 offset:0x2c00
	v_max3_f32 v218, v218, v138, v139
	v_max3_f32 v218, v218, v140, v141
	s_waitcnt lgkmcnt(6)
	v_mfma_f32_32x32x16_bf16 v[18:33], v[182:185], v[240:243], v[18:33]
	ds_read_b64_tr_b16 v[240:241], v190 offset:0x2600
	ds_read_b64_tr_b16 v[242:243], v190 offset:0x2e00
	v_max3_f32 v218, v218, v142, v143
	v_max3_f32 v218, v218, v144, v145
	s_waitcnt lgkmcnt(6)
	v_mfma_f32_32x32x16_bf16 v[2:17], v[198:201], v[206:209], v[2:17]
	ds_read_b64_tr_b16 v[206:207], v190 offset:0x3000
	ds_read_b64_tr_b16 v[208:209], v190 offset:0x3800
	v_max3_f32 v218, v218, v98, v99
	v_max3_f32 v218, v218, v100, v101
	s_waitcnt lgkmcnt(6)
	v_mfma_f32_32x32x16_bf16 v[50:65], v[198:201], v[232:235], v[50:65]
	ds_read_b64_tr_b16 v[232:233], v190 offset:0x3200
	ds_read_b64_tr_b16 v[234:235], v190 offset:0x3a00
	v_max3_f32 v218, v218, v102, v103
	v_max3_f32 v218, v218, v104, v105
	s_waitcnt lgkmcnt(6)
	v_mfma_f32_32x32x16_bf16 v[34:49], v[198:201], v[236:239], v[34:49]
	ds_read_b64_tr_b16 v[236:237], v190 offset:0x3400
	ds_read_b64_tr_b16 v[238:239], v190 offset:0x3c00
	v_max3_f32 v218, v218, v106, v107
	s_waitcnt lgkmcnt(6)
	v_mfma_f32_32x32x16_bf16 v[18:33], v[198:201], v[240:243], v[18:33]
	ds_read_b64_tr_b16 v[240:241], v190 offset:0x3600
	ds_read_b64_tr_b16 v[242:243], v190 offset:0x3e00
	v_max3_f32 v218, v218, v108, v109
	s_waitcnt lgkmcnt(6)
	v_mfma_f32_32x32x16_bf16 v[2:17], v[202:205], v[206:209], v[2:17]
	v_max3_f32 v218, v218, v110, v111
	s_waitcnt lgkmcnt(4)
	v_mfma_f32_32x32x16_bf16 v[50:65], v[202:205], v[232:235], v[50:65]
	v_max3_f32 v218, v218, v112, v113
	s_waitcnt lgkmcnt(2)
	v_mfma_f32_32x32x16_bf16 v[34:49], v[202:205], v[236:239], v[34:49]
	v_mov_b32_e32 v219, v218
	s_waitcnt lgkmcnt(0)
	v_mfma_f32_32x32x16_bf16 v[18:33], v[202:205], v[240:243], v[18:33]
	v_permlane32_swap_b32_e32 v218, v219
	v_max_f32_e32 v179, v218, v219
	s_branch .Ljoin_g2
.Lslow_g2:
	ds_read_b128 v[206:209], v195 offset:40960
	ds_read_b128 v[98:101], v195 offset:32768
	v_exp_f32_e32 v114, v114
	v_exp_f32_e32 v115, v115
	v_exp_f32_e32 v116, v116
	v_exp_f32_e32 v117, v117
	s_waitcnt lgkmcnt(0)
	v_mfma_f32_32x32x16_bf16 v[130:145], v[98:101], v[174:177], v[82:97]
	v_exp_f32_e32 v118, v118
	v_exp_f32_e32 v119, v119
	v_exp_f32_e32 v120, v120
	v_exp_f32_e32 v121, v121
	v_exp_f32_e32 v122, v122
	v_exp_f32_e32 v123, v123
	v_exp_f32_e32 v124, v124
	v_mfma_f32_32x32x16_bf16 v[98:113], v[206:209], v[174:177], v[82:97]
	ds_read_b128 v[206:209], v211 offset:40960
	ds_read_b128 v[230:233], v211 offset:32768
	v_exp_f32_e32 v125, v125
	v_exp_f32_e32 v126, v126
	v_exp_f32_e32 v127, v127
	v_exp_f32_e32 v128, v128
	v_exp_f32_e32 v129, v129
	s_waitcnt lgkmcnt(1)
	v_mfma_f32_32x32x16_bf16 v[98:113], v[206:209], v[170:173], v[98:113]
	s_waitcnt lgkmcnt(0)
	v_mfma_f32_32x32x16_bf16 v[130:145], v[230:233], v[170:173], v[130:145]
	ds_read_b128 v[206:209], v210 offset:40960
	ds_read_b128 v[230:233], v210 offset:32768
	s_waitcnt lgkmcnt(1)
	v_mfma_f32_32x32x16_bf16 v[98:113], v[206:209], v[166:169], v[98:113]
	s_waitcnt lgkmcnt(0)
	v_mfma_f32_32x32x16_bf16 v[130:145], v[230:233], v[166:169], v[130:145]
	ds_read_b128 v[206:209], v197 offset:40960
	ds_read_b128 v[230:233], v197 offset:32768
	s_waitcnt lgkmcnt(1)
	v_mfma_f32_32x32x16_bf16 v[98:113], v[206:209], v[162:165], v[98:113]
	s_waitcnt lgkmcnt(0)
	v_mfma_f32_32x32x16_bf16 v[130:145], v[230:233], v[162:165], v[130:145]
	ds_read_b128 v[206:209], v196 offset:40960
	ds_read_b128 v[230:233], v196 offset:32768
	s_waitcnt lgkmcnt(1)
	v_mfma_f32_32x32x16_bf16 v[98:113], v[206:209], v[158:161], v[98:113]
	s_waitcnt lgkmcnt(0)
	v_mfma_f32_32x32x16_bf16 v[130:145], v[230:233], v[158:161], v[130:145]
	ds_read_b128 v[206:209], v222 offset:40960
	ds_read_b128 v[230:233], v222 offset:32768
	s_waitcnt lgkmcnt(1)
	v_mfma_f32_32x32x16_bf16 v[98:113], v[206:209], v[154:157], v[98:113]
	s_waitcnt lgkmcnt(0)
	v_mfma_f32_32x32x16_bf16 v[130:145], v[230:233], v[154:157], v[130:145]
	ds_read_b128 v[206:209], v223 offset:40960
	ds_read_b128 v[230:233], v223 offset:32768
	s_waitcnt lgkmcnt(1)
; __device__ __forceinline__ void finishSM(f32x16& p0, f32x16& p1, float alpha, float& l_reg, bf16x8& pa0, bf16x8& pa1, bf16x8& pa2, bf16x8& pa3) {
; #pragma unroll
;   for (int r = 0; r < 16; ++r) p1[r] = __builtin_amdgcn_exp2f(p1[r]);
;   float ps = 0;
; #pragma unroll
;   for (int r = 0; r < 16; ++r) ps += p0[r];
; #pragma unroll
;   for (int r = 0; r < 16; ++r) ps += p1[r];
;   { auto rr = __builtin_amdgcn_permlane32_swap(__float_as_uint(ps), __float_as_uint(ps), false, false);
;     ps = __uint_as_float(rr[0]) + __uint_as_float(rr[1]); }
;   l_reg = l_reg * alpha + ps;
;     ...
;   PK4(p0, 0, pa0); PK4(p0, 8, pa1); PK4(p1, 0, pa2); PK4(p1, 8, pa3);
;     ...
; }
; template <int DQK> __device__ __forceinline__ void qkt(f32x16& p0, f32x16& p1, const char* Ks, const bf16x8* qr, int r32, int hi, const f32x16& negm) {
; #pragma unroll
;   for (int d0 = 0; d0 < DQK / 16; ++d0) { const int cb = (d0 * 16 + hi * 8) * 2;
;     const bf16x8 b0 = *reinterpret_cast<const bf16x8*>(Ks + (DQK == 128 ? KSWZ(r32, cb) : KSWZ64(r32, cb)));
;     const bf16x8 b1 = *reinterpret_cast<const bf16x8*>(Ks + (DQK == 128 ? KSWZ(32 + r32, cb) : KSWZ64(32 + r32, cb)));
;     if (d0 == 0) { p0 = __builtin_amdgcn_mfma_f32_32x32x16_bf16(b0, qr[0], negm, 0, 0, 0); p1 = __builtin_amdgcn_mfma_f32_32x32x16_bf16(b1, qr[0], negm, 0, 0, 0); }
;     else { p0 = __builtin_amdgcn_mfma_f32_32x32x16_bf16(b0, qr[d0], p0, 0, 0, 0); p1 = __builtin_amdgcn_mfma_f32_32x32x16_bf16(b1, qr[d0], p1, 0, 0, 0); } }
; }
; __device__ __forceinline__ int v_st(int k, int c) { const int kk = (k & ~0xC) | ((k & 4) << 1) | ((k & 8) >> 1); return ((kk >> 3) * 4 + (c >> 5)) * 512 + ((kk & 7) * 32 + (c & 31)) * 2; }
; __device__ __forceinline__ int v_rd_base(int lane) { return ((lane & 3) << 3) | (((lane >> 2) & 3) << 6) | (((lane >> 4) & 1) << 5) | (((lane >> 5) & 1) << 8); }
; template <int OFF> __device__ __forceinline__ s16x4 tr_read(int vb) {
;   s16x4 r; asm volatile("ds_read_b64_tr_b16 %0, %1 offset:%2" : "=&v"(r) : "v"(vb), "i"(OFF) : "memory"); return r;
; }
; template <int D0> __device__ __forceinline__ void pv_one(f32x16& od, int vb, bf16x8 pa0, bf16x8 pa1, bf16x8 pa2, bf16x8 pa3) {
;   const s16x4 l0 = tr_read<v_rd_off(D0, 0, 0)>(vb), h0 = tr_read<v_rd_off(D0, 0, 1)>(vb), l1 = tr_read<v_rd_off(D0, 1, 0)>(vb), h1 = tr_read<v_rd_off(D0, 1, 1)>(vb);
	v_mfma_f32_32x32x16_bf16 v[98:113], v[206:209], v[150:153], v[98:113]
	s_waitcnt lgkmcnt(0)
	v_mfma_f32_32x32x16_bf16 v[130:145], v[230:233], v[150:153], v[130:145]
	ds_read_b128 v[206:209], v224 offset:40960
	ds_read_b128 v[230:233], v224 offset:32768
	s_waitcnt lgkmcnt(1)
	v_mfma_f32_32x32x16_bf16 v[98:113], v[206:209], v[146:149], v[98:113]
	v_add_f32_e32 v206, 0, v178
	v_add_f32_e32 v206, v205, v206
	v_add_f32_e32 v206, v179, v206
	v_add_f32_e32 v206, v204, v206
	v_add_f32_e32 v206, v180, v206
	v_add_f32_e32 v206, v203, v206
	v_add_f32_e32 v206, v181, v206
	v_add_f32_e32 v206, v202, v206
	v_add_f32_e32 v206, v182, v206
	v_add_f32_e32 v206, v201, v206
	v_add_f32_e32 v206, v183, v206
	v_add_f32_e32 v206, v200, v206
	v_add_f32_e32 v206, v184, v206
	v_add_f32_e32 v206, v199, v206
	v_add_f32_e32 v206, v185, v206
	v_add_f32_e32 v206, v198, v206
	v_add_f32_e32 v206, v114, v206
	v_add_f32_e32 v206, v115, v206
	v_add_f32_e32 v206, v116, v206
	v_add_f32_e32 v206, v117, v206
	v_add_f32_e32 v206, v118, v206
	v_add_f32_e32 v206, v119, v206
	v_add_f32_e32 v206, v120, v206
	v_add_f32_e32 v206, v121, v206
	v_add_f32_e32 v206, v122, v206
	v_add_f32_e32 v206, v123, v206
	s_waitcnt lgkmcnt(0)
	v_mfma_f32_32x32x16_bf16 v[130:145], v[230:233], v[146:149], v[130:145]
	v_add_f32_e32 v206, v124, v206
	v_add_f32_e32 v206, v125, v206
	v_add_f32_e32 v206, v126, v206
	v_add_f32_e32 v206, v127, v206
	v_add_f32_e32 v206, v128, v206
	v_add_f32_e32 v230, v129, v206
	v_mov_b32_e32 v231, v230
	s_nop 1
	v_permlane32_swap_b32_e32 v230, v231
	v_cvt_pk_bf16_f32 v178, v178, v205
	v_cvt_pk_bf16_f32 v179, v179, v204
	v_cvt_pk_bf16_f32 v180, v180, v203
	v_cvt_pk_bf16_f32 v181, v181, v202
	v_cvt_pk_bf16_f32 v182, v182, v201
	v_cvt_pk_bf16_f32 v183, v183, v200
	v_cvt_pk_bf16_f32 v184, v184, v199
	v_cvt_pk_bf16_f32 v185, v185, v198
	v_cvt_pk_bf16_f32 v198, v114, v115
	v_cvt_pk_bf16_f32 v199, v116, v117
	v_cvt_pk_bf16_f32 v200, v118, v119
	v_cvt_pk_bf16_f32 v201, v120, v121
	v_cvt_pk_bf16_f32 v202, v122, v123
	v_cvt_pk_bf16_f32 v203, v124, v125
	v_cvt_pk_bf16_f32 v204, v126, v127
	v_cvt_pk_bf16_f32 v205, v128, v129
	s_nop 0
	v_permlane32_swap_b32_e32 v178, v180
	v_permlane32_swap_b32_e32 v179, v181
	v_permlane32_swap_b32_e32 v182, v184
	v_permlane32_swap_b32_e32 v183, v185
	v_permlane32_swap_b32_e32 v198, v200
	v_permlane32_swap_b32_e32 v199, v201
	v_permlane32_swap_b32_e32 v202, v204
	v_permlane32_swap_b32_e32 v203, v205
	v_add_co_u32_e32 v118, vcc, s80, v186
	s_nop 1
	v_addc_co_u32_e32 v119, vcc, 0, v187, vcc
	v_add_co_u32_e32 v122, vcc, s81, v186
	s_nop 1
	v_addc_co_u32_e32 v123, vcc, 0, v187, vcc
	global_load_dwordx4 v[114:117], v[118:119], off offset:512
	s_nop 0
	global_load_dwordx4 v[118:121], v[118:119], off
	s_nop 0
	global_load_dwordx4 v[126:129], v[122:123], off offset:512
	s_nop 0
	global_load_dwordx4 v[122:125], v[122:123], off
	ds_read_b64_tr_b16 v[206:207], v190 offset:0
	ds_read_b64_tr_b16 v[208:209], v190 offset:0x800
	ds_read_b64_tr_b16 v[232:233], v190 offset:0x1000
	ds_read_b64_tr_b16 v[234:235], v190 offset:0x1800
	ds_read_b64_tr_b16 v[236:237], v190 offset:0x2000
	ds_read_b64_tr_b16 v[238:239], v190 offset:0x2800
	ds_read_b64_tr_b16 v[240:241], v190 offset:0x3000
	ds_read_b64_tr_b16 v[242:243], v190 offset:0x3800
	s_waitcnt lgkmcnt(0)
	s_nop 0
	v_mfma_f32_32x32x16_bf16 v[2:17], v[178:181], v[206:209], v[2:17]
	ds_read_b64_tr_b16 v[206:207], v190 offset:0x200
	ds_read_b64_tr_b16 v[208:209], v190 offset:0xa00
	v_mfma_f32_32x32x16_bf16 v[2:17], v[182:185], v[232:235], v[2:17]
	ds_read_b64_tr_b16 v[232:233], v190 offset:0x1200
	ds_read_b64_tr_b16 v[234:235], v190 offset:0x1a00
	v_mfma_f32_32x32x16_bf16 v[2:17], v[198:201], v[236:239], v[2:17]
	ds_read_b64_tr_b16 v[236:237], v190 offset:0x2200
	ds_read_b64_tr_b16 v[238:239], v190 offset:0x2a00
	v_mfma_f32_32x32x16_bf16 v[2:17], v[202:205], v[240:243], v[2:17]
	ds_read_b64_tr_b16 v[240:241], v190 offset:0x3200
	ds_read_b64_tr_b16 v[242:243], v190 offset:0x3a00
	s_waitcnt lgkmcnt(0)
	v_mfma_f32_32x32x16_bf16 v[50:65], v[178:181], v[206:209], v[50:65]
	ds_read_b64_tr_b16 v[206:207], v190 offset:0x400
	ds_read_b64_tr_b16 v[208:209], v190 offset:0xc00
	v_mfma_f32_32x32x16_bf16 v[50:65], v[182:185], v[232:235], v[50:65]
	ds_read_b64_tr_b16 v[232:233], v190 offset:0x1400
	ds_read_b64_tr_b16 v[234:235], v190 offset:0x1c00
	v_mfma_f32_32x32x16_bf16 v[50:65], v[198:201], v[236:239], v[50:65]
	ds_read_b64_tr_b16 v[236:237], v190 offset:0x2400
	ds_read_b64_tr_b16 v[238:239], v190 offset:0x2c00
	v_mfma_f32_32x32x16_bf16 v[50:65], v[202:205], v[240:243], v[50:65]
	ds_read_b64_tr_b16 v[240:241], v190 offset:0x3400
	ds_read_b64_tr_b16 v[242:243], v190 offset:0x3c00
	s_waitcnt lgkmcnt(0)
	v_mfma_f32_32x32x16_bf16 v[34:49], v[178:181], v[206:209], v[34:49]
	ds_read_b64_tr_b16 v[206:207], v190 offset:0x600
	ds_read_b64_tr_b16 v[208:209], v190 offset:0xe00
	v_mfma_f32_32x32x16_bf16 v[34:49], v[182:185], v[232:235], v[34:49]
	ds_read_b64_tr_b16 v[232:233], v190 offset:0x1600
	ds_read_b64_tr_b16 v[234:235], v190 offset:0x1e00
	v_mfma_f32_32x32x16_bf16 v[34:49], v[198:201], v[236:239], v[34:49]
	ds_read_b64_tr_b16 v[236:237], v190 offset:0x2600
	ds_read_b64_tr_b16 v[238:239], v190 offset:0x2e00
	v_mfma_f32_32x32x16_bf16 v[34:49], v[202:205], v[240:243], v[34:49]
	ds_read_b64_tr_b16 v[240:241], v190 offset:0x3600
	ds_read_b64_tr_b16 v[242:243], v190 offset:0x3e00
	s_waitcnt lgkmcnt(0)
	v_mfma_f32_32x32x16_bf16 v[18:33], v[178:181], v[206:209], v[18:33]
	s_cmp_le_u32 s14, s16
	v_mfma_f32_32x32x16_bf16 v[18:33], v[182:185], v[232:235], v[18:33]
	v_mfma_f32_32x32x16_bf16 v[18:33], v[198:201], v[236:239], v[18:33]
	v_mfma_f32_32x32x16_bf16 v[18:33], v[202:205], v[240:243], v[18:33]
	s_cbranch_scc0 .LBB0_88

; #define SBAR() __builtin_amdgcn_sched_barrier(0)
; #define NEGM(t) do { if (BIAS) { const float c_ = cinit<BIAS, VIRT>((t), qw0, lut); if (c_ != c_cur) { c_cur = c_; const float nm_ = c_ - m_reg; _Pragma("unroll") for (int r = 0; r < 16; ++r) negm[r] = nm_; } } } while (0)
; template <int DQK, bool BIAS, bool VIRT = false>
; __device__ __forceinline__ void attn_pass(const bf16_t* __restrict__ Qb, const bf16_t* __restrict__ Kh, const bf16_t* __restrict__ Vh, int L, int NT, int qw0, const float* lut, f32x16 (&o)[4], char* lds, int nact) {
;     ...
;   }
;   NEGM(NT - 1); SBAR(); qkt<DQK>(pB0, pB1, K_lds + SHM_K, qr, r32, hi, negm);
.Lexit_fix128:
	v_mov_b64_e32 v[66:67], v[82:83]
	v_mov_b64_e32 v[68:69], v[84:85]
	v_mov_b64_e32 v[70:71], v[86:87]
	v_mov_b64_e32 v[72:73], v[88:89]
	v_mov_b64_e32 v[74:75], v[90:91]
	v_mov_b64_e32 v[76:77], v[92:93]
	v_mov_b64_e32 v[78:79], v[94:95]
	v_mov_b64_e32 v[80:81], v[96:97]
	s_branch .LBB0_152

; #define SBAR() __builtin_amdgcn_sched_barrier(0)
; template <bool FIRST> __device__ __forceinline__ void partialSM(f32x16& p0, f32x16& p1, float& m_reg, float& alpha, f32x16& negm, float c_cur) {
;   float pmax = p0[0];
; #pragma unroll
;   for (int r = 1; r < 16; ++r) pmax = fmaxf(pmax, p0[r]);
; #pragma unroll
;   for (int r = 0; r < 16; ++r) pmax = fmaxf(pmax, p1[r]);
;   { auto rr = __builtin_amdgcn_permlane32_swap(__float_as_uint(pmax), __float_as_uint(pmax), false, false);
;     pmax = fmaxf(__uint_as_float(rr[0]), __uint_as_float(rr[1])); }
; template <int D0> __device__ __forceinline__ void pv_one(f32x16& od, int vb, bf16x8 pa0, bf16x8 pa1, bf16x8 pa2, bf16x8 pa3) {
;   const s16x4 l0 = tr_read<v_rd_off(D0, 0, 0)>(vb), h0 = tr_read<v_rd_off(D0, 0, 1)>(vb), l1 = tr_read<v_rd_off(D0, 1, 0)>(vb), h1 = tr_read<v_rd_off(D0, 1, 1)>(vb);
;   const s16x4 l2 = tr_read<v_rd_off(D0, 2, 0)>(vb), h2 = tr_read<v_rd_off(D0, 2, 1)>(vb), l3 = tr_read<v_rd_off(D0, 3, 0)>(vb), h3 = tr_read<v_rd_off(D0, 3, 1)>(vb);
;   asm volatile("s_waitcnt lgkmcnt(0)" ::: "memory"); SBAR();
;     ...
;   od = __builtin_amdgcn_mfma_f32_32x32x16_bf16(pa0, PK(l0, h0), od, 0, 0, 0);
;   od = __builtin_amdgcn_mfma_f32_32x32x16_bf16(pa1, PK(l1, h1), od, 0, 0, 0);
;   od = __builtin_amdgcn_mfma_f32_32x32x16_bf16(pa2, PK(l2, h2), od, 0, 0, 0);
;   od = __builtin_amdgcn_mfma_f32_32x32x16_bf16(pa3, PK(l3, h3), od, 0, 0, 0);
;     ...
; }
; __device__ __forceinline__ void pv_d0(f32x16* o, int vb, bf16x8 pa0, bf16x8 pa1, bf16x8 pa2, bf16x8 pa3) {
;   pv_one<0>(o[0], vb, pa0, pa1, pa2, pa3); pv_one<1>(o[1], vb, pa0, pa1, pa2, pa3); pv_one<2>(o[2], vb, pa0, pa1, pa2, pa3); pv_one<3>(o[3], vb, pa0, pa1, pa2, pa3);
.Lcret_f1:
	s_waitcnt lgkmcnt(4)
	v_mfma_f32_32x32x16_bf16 v[84:99], v[116:119], v[162:165], v[236:251]
	v_mfma_f32_32x32x16_bf16 v[116:131], v[180:183], v[162:165], v[236:251]
	ds_read_b128 v[180:183], v226 offset:53248
	v_permlane32_swap_b32_e32 v76, v78
	v_permlane32_swap_b32_e32 v77, v79
	v_permlane32_swap_b32_e32 v80, v82
	v_permlane32_swap_b32_e32 v81, v83
	v_lshl_add_u64 v[148:149], v[194:195], 0, s[0:1]
	v_lshl_add_u64 v[196:197], v[192:193], 0, s[0:1]
	s_mov_b32 s4, 0x102b1000
	v_add_co_u32_e64 v132, s[4:5], s4, v148
	s_waitcnt lgkmcnt(3)
	v_mfma_f32_32x32x16_bf16 v[116:131], v[184:187], v[158:161], v[116:131]
	v_addc_co_u32_e64 v133, s[4:5], 0, v149, s[4:5]
	s_mov_b32 s4, 0x102f9000
	v_add_co_u32_e64 v202, s[4:5], s4, v148
	v_mfma_f32_32x32x16_bf16 v[84:99], v[68:71], v[158:161], v[84:99]
	ds_read_b128 v[184:187], v226 offset:49152
	v_addc_co_u32_e64 v203, s[4:5], 0, v149, s[4:5]
	s_mov_b32 s4, 0x102b0000
	v_add_co_u32_e64 v204, s[4:5], s4, v196
	s_waitcnt lgkmcnt(2)
	v_mfma_f32_32x32x16_bf16 v[116:131], v[72:75], v[154:157], v[116:131]
	v_addc_co_u32_e64 v205, s[4:5], 0, v197, s[4:5]
	v_mfma_f32_32x32x16_bf16 v[84:99], v[206:209], v[154:157], v[84:99]
	ds_read_b64_tr_b16 v[134:135], v223 offset:0
	ds_read_b64_tr_b16 v[136:137], v223 offset:0x800
	ds_read_b64_tr_b16 v[138:139], v223 offset:0x200
	ds_read_b64_tr_b16 v[140:141], v223 offset:0xa00
	ds_read_b64_tr_b16 v[142:143], v223 offset:0x400
	ds_read_b64_tr_b16 v[144:145], v223 offset:0xc00
	ds_read_b64_tr_b16 v[198:199], v223 offset:0x600
	ds_read_b64_tr_b16 v[200:201], v223 offset:0xe00
	s_waitcnt lgkmcnt(8)
	v_mfma_f32_32x32x16_bf16 v[116:131], v[180:183], v[150:153], v[116:131]
	v_mfma_f32_32x32x16_bf16 v[84:99], v[184:187], v[150:153], v[84:99]
	global_load_dwordx4 v[178:181], v[132:133], off
	global_load_dwordx4 v[182:185], v[202:203], off
	global_load_dwordx4 v[186:189], v[204:205], off offset:2048
	s_waitcnt lgkmcnt(6)
	v_mfma_f32_32x32x16_bf16 v[50:65], v[76:79], v[134:137], v[50:65]
	ds_read_b64_tr_b16 v[134:135], v223 offset:0x1000
	ds_read_b64_tr_b16 v[136:137], v223 offset:0x1800
	v_exp_f32_e32 v68, v100
	v_exp_f32_e32 v69, v101
	v_add_f32_e32 v0, v68, v0
	s_waitcnt lgkmcnt(6)
	v_mfma_f32_32x32x16_bf16 v[34:49], v[76:79], v[138:141], v[34:49]
	ds_read_b64_tr_b16 v[138:139], v223 offset:0x1200
	ds_read_b64_tr_b16 v[140:141], v223 offset:0x1a00
	v_exp_f32_e32 v70, v102
	v_add_f32_e32 v0, v69, v0
	v_exp_f32_e32 v71, v103
	v_add_f32_e32 v0, v70, v0
	s_waitcnt lgkmcnt(6)
	v_mfma_f32_32x32x16_bf16 v[18:33], v[76:79], v[142:145], v[18:33]
	ds_read_b64_tr_b16 v[142:143], v223 offset:0x1400
	ds_read_b64_tr_b16 v[144:145], v223 offset:0x1c00
	v_exp_f32_e32 v72, v104
	v_add_f32_e32 v0, v71, v0
	v_exp_f32_e32 v73, v105
	v_add_f32_e32 v0, v72, v0
	s_waitcnt lgkmcnt(6)
	v_mfma_f32_32x32x16_bf16 v[2:17], v[76:79], v[198:201], v[2:17]
	ds_read_b64_tr_b16 v[198:199], v223 offset:0x1600
	ds_read_b64_tr_b16 v[200:201], v223 offset:0x1e00
	v_exp_f32_e32 v74, v106
	v_add_f32_e32 v0, v73, v0
	v_exp_f32_e32 v75, v107
	v_add_f32_e32 v0, v74, v0
	v_add_f32_e32 v0, v75, v0
	s_waitcnt lgkmcnt(6)
	v_mfma_f32_32x32x16_bf16 v[50:65], v[80:83], v[134:137], v[50:65]
	ds_read_b64_tr_b16 v[134:135], v223 offset:0x2000
	ds_read_b64_tr_b16 v[136:137], v223 offset:0x2800
	v_cvt_pk_bf16_f32 v100, v68, v69
	v_cvt_pk_bf16_f32 v101, v70, v71
	v_cvt_pk_bf16_f32 v102, v72, v73
	v_cvt_pk_bf16_f32 v103, v74, v75
	s_waitcnt lgkmcnt(6)
	v_mfma_f32_32x32x16_bf16 v[34:49], v[80:83], v[138:141], v[34:49]
	ds_read_b64_tr_b16 v[138:139], v223 offset:0x2200
	ds_read_b64_tr_b16 v[140:141], v223 offset:0x2a00
	v_exp_f32_e32 v68, v108
	v_exp_f32_e32 v69, v109
	v_permlane32_swap_b32_e32 v100, v102
	v_permlane32_swap_b32_e32 v101, v103
	s_waitcnt lgkmcnt(6)
	v_mfma_f32_32x32x16_bf16 v[18:33], v[80:83], v[142:145], v[18:33]
	ds_read_b64_tr_b16 v[142:143], v223 offset:0x2400
	ds_read_b64_tr_b16 v[144:145], v223 offset:0x2c00
	v_exp_f32_e32 v70, v110
	v_exp_f32_e32 v71, v111
	v_exp_f32_e32 v72, v112
	s_waitcnt lgkmcnt(6)
	v_mfma_f32_32x32x16_bf16 v[2:17], v[80:83], v[198:201], v[2:17]
	ds_read_b64_tr_b16 v[198:199], v223 offset:0x2600
	ds_read_b64_tr_b16 v[200:201], v223 offset:0x2e00
	v_exp_f32_e32 v73, v113
	v_exp_f32_e32 v74, v114
	v_exp_f32_e32 v75, v115
	s_waitcnt lgkmcnt(6)
	v_mfma_f32_32x32x16_bf16 v[50:65], v[100:103], v[134:137], v[50:65]
	ds_read_b64_tr_b16 v[134:135], v223 offset:0x3000
	ds_read_b64_tr_b16 v[136:137], v223 offset:0x3800
	v_add_f32_e32 v0, v68, v0
	v_add_f32_e32 v0, v69, v0
	v_add_f32_e32 v0, v70, v0
	v_add_f32_e32 v0, v71, v0
	s_waitcnt lgkmcnt(6)
	v_mfma_f32_32x32x16_bf16 v[34:49], v[100:103], v[138:141], v[34:49]
	ds_read_b64_tr_b16 v[138:139], v223 offset:0x3200
	ds_read_b64_tr_b16 v[140:141], v223 offset:0x3a00
	v_add_f32_e32 v0, v72, v0
	v_add_f32_e32 v0, v73, v0
	v_add_f32_e32 v0, v74, v0
	v_add_f32_e32 v0, v75, v0
	v_mov_b32_e32 v231, v0
	s_waitcnt lgkmcnt(6)
	v_mfma_f32_32x32x16_bf16 v[18:33], v[100:103], v[142:145], v[18:33]
	ds_read_b64_tr_b16 v[142:143], v223 offset:0x3400
	ds_read_b64_tr_b16 v[144:145], v223 offset:0x3c00
	v_cvt_pk_bf16_f32 v104, v68, v69
	v_cvt_pk_bf16_f32 v105, v70, v71
	v_cvt_pk_bf16_f32 v106, v72, v73
	v_cvt_pk_bf16_f32 v107, v74, v75
	v_permlane32_swap_b32_e32 v0, v231
	s_waitcnt lgkmcnt(6)
	v_mfma_f32_32x32x16_bf16 v[2:17], v[100:103], v[198:201], v[2:17]
	ds_read_b64_tr_b16 v[198:199], v223 offset:0x3600
	ds_read_b64_tr_b16 v[200:201], v223 offset:0x3e00
	v_permlane32_swap_b32_e32 v104, v106
	v_permlane32_swap_b32_e32 v105, v107
	v_max_f32_e32 v132, v84, v85
	v_max3_f32 v132, v132, v86, v87
	v_max3_f32 v132, v132, v88, v89
	s_waitcnt lgkmcnt(6)
	v_mfma_f32_32x32x16_bf16 v[50:65], v[104:107], v[134:137], v[50:65]
	v_max3_f32 v132, v132, v90, v91
	v_max3_f32 v132, v132, v92, v93
	v_max3_f32 v132, v132, v94, v95
	v_max3_f32 v132, v132, v96, v97
	v_max3_f32 v132, v132, v98, v99
	s_waitcnt lgkmcnt(4)
	v_mfma_f32_32x32x16_bf16 v[34:49], v[104:107], v[138:141], v[34:49]
	v_max3_f32 v132, v132, v116, v117
	v_max3_f32 v132, v132, v118, v119
	v_max3_f32 v132, v132, v120, v121
	v_max3_f32 v132, v132, v122, v123
	v_max3_f32 v132, v132, v124, v125
	s_waitcnt lgkmcnt(2)
	v_mfma_f32_32x32x16_bf16 v[18:33], v[104:107], v[142:145], v[18:33]
	v_max3_f32 v132, v132, v126, v127
	v_max3_f32 v132, v132, v128, v129
	v_max3_f32 v132, v132, v130, v131
	v_mov_b32_e32 v133, v132
	s_waitcnt lgkmcnt(0)
	v_mfma_f32_32x32x16_bf16 v[2:17], v[104:107], v[198:201], v[2:17]
	v_permlane32_swap_b32_e32 v132, v133
	v_max_f32_e32 v100, v132, v133
	s_branch .Ljoin_h1

; #define SWRITE(b, i) do { *(bf16x8*)(V_lds + (b) * SHM_V + vst0) = sr_[i].vs0; *(bf16x8*)(V_lds + (b) * SHM_V + vst1) = sr_[i].vs1; \
;     if (DQK == 128) { *(bf16x8*)(K_lds + (b) * SHM_K + KSWZ(sr, sc * 2)) = sr_[i].ks0; *(bf16x8*)(K_lds + (b) * SHM_K + KSWZ(32 + sr, sc * 2)) = sr_[i].ks1; } \
;     else { *(bf16x8*)(K_lds + (b) * SHM_K + KSWZ64(kr, kc * 2)) = sr_[i].ks0; } } while (0)
; #define SWAIT() do { if (SDEPTH == 1) asm volatile("s_waitcnt vmcnt(0)" ::: "memory"); else if (DQK == 128) asm volatile("s_waitcnt vmcnt(4)" ::: "memory"); else asm volatile("s_waitcnt vmcnt(3)" ::: "memory"); } while (0)
; #define RESC(a) do { if (__any((a) < 1.f)) { if (hi == 0) al_l[r32] = (a); asm volatile("s_waitcnt lgkmcnt(0)" ::: "memory"); \
;     _Pragma("unroll") for (int d = 0; d < 4; ++d) _Pragma("unroll") for (int r = 0; r < 16; ++r) o[d][r] *= al_l[crow(r, hi)]; } } while (0)
; template <int DQK, bool BIAS, bool VIRT = false>
; __device__ __forceinline__ void attn_pass(const bf16_t* __restrict__ Qb, const bf16_t* __restrict__ Kh, const bf16_t* __restrict__ Vh, int L, int NT, int qw0, const float* lut, f32x16 (&o)[4], char* lds, int nact) {
;     ...
;     __syncthreads(); SWAIT(); SWRITE(0, SE);
;     RESC(alB); __syncthreads();
.LBB0_223:
	v_mov_b32_e32 v232, 1.0
	v_mov_b32_e32 v234, v233
.LBB0_225:
	s_barrier
	s_waitcnt vmcnt(3)
	v_cmp_gt_f32_e32 vcc, 1.0, v232
	s_waitcnt vmcnt(3)
	ds_write_b128 v212, v[166:169]
	ds_write_b128 v213, v[170:173]
	ds_write_b128 v229, v[174:177] offset:32768
	s_cbranch_vccz .LBB0_229
	s_and_saveexec_b64 s[4:5], s[40:41]
	ds_write_b32 v191, v232 offset:128
	s_or_b64 exec, exec, s[4:5]
	s_waitcnt lgkmcnt(0)
	v_add_u32_e32 v68, s24, v190
	ds_read_b128 v[70:73], v68 offset:128
	ds_read_b128 v[74:77], v68 offset:160
	ds_read_b128 v[78:81], v68 offset:192
	ds_read_b128 v[100:103], v68 offset:224
	s_waitcnt lgkmcnt(3)
	v_pk_mul_f32 v[34:35], v[70:71], v[34:35]
	v_pk_mul_f32 v[36:37], v[36:37], v[72:73]
	s_waitcnt lgkmcnt(2)
	v_pk_mul_f32 v[38:39], v[38:39], v[74:75]
	v_pk_mul_f32 v[40:41], v[40:41], v[76:77]
	s_waitcnt lgkmcnt(1)
	v_pk_mul_f32 v[42:43], v[42:43], v[78:79]
	v_pk_mul_f32 v[44:45], v[44:45], v[80:81]
	s_waitcnt lgkmcnt(0)
	v_pk_mul_f32 v[46:47], v[46:47], v[100:101]
	v_pk_mul_f32 v[62:63], v[62:63], v[100:101]
	v_pk_mul_f32 v[58:59], v[58:59], v[78:79]
	v_pk_mul_f32 v[54:55], v[54:55], v[74:75]
	v_pk_mul_f32 v[64:65], v[64:65], v[102:103]
	v_pk_mul_f32 v[60:61], v[60:61], v[80:81]
	v_pk_mul_f32 v[56:57], v[56:57], v[76:77]
	v_pk_mul_f32 v[52:53], v[52:53], v[72:73]
	v_pk_mul_f32 v[50:51], v[50:51], v[70:71]
	v_pk_mul_f32 v[48:49], v[48:49], v[102:103]
	v_pk_mul_f32 v[2:3], v[70:71], v[2:3]
	v_pk_mul_f32 v[4:5], v[4:5], v[72:73]
	v_pk_mul_f32 v[6:7], v[6:7], v[74:75]
	v_pk_mul_f32 v[8:9], v[8:9], v[76:77]
	v_pk_mul_f32 v[10:11], v[10:11], v[78:79]
	v_pk_mul_f32 v[12:13], v[12:13], v[80:81]
	v_pk_mul_f32 v[14:15], v[14:15], v[100:101]
	v_pk_mul_f32 v[30:31], v[30:31], v[100:101]
	v_pk_mul_f32 v[26:27], v[26:27], v[78:79]
	v_pk_mul_f32 v[22:23], v[22:23], v[74:75]
	v_pk_mul_f32 v[32:33], v[32:33], v[102:103]
	v_pk_mul_f32 v[28:29], v[28:29], v[80:81]
	v_pk_mul_f32 v[24:25], v[24:25], v[76:77]
	v_pk_mul_f32 v[20:21], v[20:21], v[72:73]
	v_pk_mul_f32 v[18:19], v[18:19], v[70:71]
	v_pk_mul_f32 v[16:17], v[16:17], v[102:103]

; #define SBAR() __builtin_amdgcn_sched_barrier(0)
; #define SLOAD(i, k0) do { sr_[i].vs0 = GLD8(&Vh[(long)((k0) + sr) * LD + sc]); sr_[i].vs1 = GLD8(&Vh[(long)((k0) + 32 + sr) * LD + sc]); \
;     if (DQK == 128) { sr_[i].ks0 = GLD8(&Kh[(long)((k0) + sr) * LD + sc]); sr_[i].ks1 = GLD8(&Kh[(long)((k0) + 32 + sr) * LD + sc]); } \
;     else { sr_[i].ks0 = GLD8(&Kh[(long)((k0) + kr) * LD + kc]); } } while (0)
; #define NEGM(t) do { if (BIAS) { const float c_ = cinit<BIAS, VIRT>((t), qw0, lut); if (c_ != c_cur) { c_cur = c_; const float nm_ = c_ - m_reg; _Pragma("unroll") for (int r = 0; r < 16; ++r) negm[r] = nm_; } } } while (0)
; template <int DQK> __device__ __forceinline__ void qkt(f32x16& p0, f32x16& p1, const char* Ks, const bf16x8* qr, int r32, int hi, const f32x16& negm) {
; #pragma unroll
;   for (int d0 = 0; d0 < DQK / 16; ++d0) { const int cb = (d0 * 16 + hi * 8) * 2;
;     const bf16x8 b0 = *reinterpret_cast<const bf16x8*>(Ks + (DQK == 128 ? KSWZ(r32, cb) : KSWZ64(r32, cb)));
;     const bf16x8 b1 = *reinterpret_cast<const bf16x8*>(Ks + (DQK == 128 ? KSWZ(32 + r32, cb) : KSWZ64(32 + r32, cb)));
;     if (d0 == 0) { p0 = __builtin_amdgcn_mfma_f32_32x32x16_bf16(b0, qr[0], negm, 0, 0, 0); p1 = __builtin_amdgcn_mfma_f32_32x32x16_bf16(b1, qr[0], negm, 0, 0, 0); }
;     else { p0 = __builtin_amdgcn_mfma_f32_32x32x16_bf16(b0, qr[d0], p0, 0, 0, 0); p1 = __builtin_amdgcn_mfma_f32_32x32x16_bf16(b1, qr[d0], p1, 0, 0, 0); } }
; }
; template <int DQK, bool BIAS, bool VIRT = false>
; __device__ __forceinline__ void attn_pass(const bf16_t* __restrict__ Qb, const bf16_t* __restrict__ Kh, const bf16_t* __restrict__ Vh, int L, int NT, int qw0, const float* lut, f32x16 (&o)[4], char* lds, int nact) {
;     ...
;     NEGM(j + 1); SBAR(); qkt<DQK>(pA0, pA1, K_lds, qr, r32, hi, negm);
;     finishSM(pB0, pB1, alB, l_reg, pa0, pa1, pa2, pa3); SBAR();
;     if (SDEPTH == 1 || j + 3 < NT) SLOAD(SE, (j + 1 + SDEPTH) * KVBLK); SBAR();
;     pv_d0(o, vb0 + SHM_V, pa0, pa1, pa2, pa3); fixup<BIAS, VIRT>(pA0, pA1, j + 1, L, qw0, r32, hi, lut); partialSM<false>(pA0, pA1, m_reg, alA, negm, c_cur);
.LBB0_235:
	s_add_i32 s4, s25, -1
	s_add_i32 s99, s19, 0xffffffa1
	s_cmp_lt_u32 s99, 0xfffffea3
	s_cbranch_scc0 .Lold_h2
	s_add_i32 s99, s18, 64
	s_cmp_le_u32 s99, s47
	s_cbranch_scc0 .Lold_h2
	ds_read_b128 v[84:87], v225 offset:36864
	ds_read_b128 v[100:103], v225 offset:32768
	ds_read_b128 v[88:91], v227 offset:36864
	ds_read_b128 v[134:137], v227 offset:32768
	ds_read_b128 v[138:141], v228 offset:36864
	ds_read_b128 v[142:145], v228 offset:32768
	v_add_f32_e32 v235, 0, v219
	v_add_f32_e32 v235, v233, v235
	v_add_f32_e32 v235, v209, v235
	v_add_f32_e32 v235, v220, v235
	v_add_f32_e32 v235, v207, v235
	v_add_f32_e32 v235, v218, v235
	v_add_f32_e32 v235, v206, v235
	v_add_f32_e32 v235, v208, v235
	v_add_f32_e32 v235, v203, v235
	v_add_f32_e32 v235, v205, v235
	v_add_f32_e32 v235, v201, v235
	v_add_f32_e32 v235, v204, v235
	v_add_f32_e32 v235, v199, v235
	v_add_f32_e32 v235, v202, v235
	v_add_f32_e32 v235, v198, v235
	v_add_f32_e32 v235, v200, v235
	v_cvt_pk_bf16_f32 v92, v219, v233
	v_cvt_pk_bf16_f32 v93, v209, v220
	v_cvt_pk_bf16_f32 v94, v207, v218
	v_cvt_pk_bf16_f32 v95, v206, v208
	v_cvt_pk_bf16_f32 v96, v203, v205
	v_cvt_pk_bf16_f32 v97, v201, v204
	v_cvt_pk_bf16_f32 v98, v199, v202
	v_cvt_pk_bf16_f32 v99, v198, v200
	s_waitcnt lgkmcnt(6)
	v_cmp_neq_f32_e32 vcc, v133, v66
	s_cbranch_vccnz .Lcupd_f2
.Lcret_f2:
	s_waitcnt lgkmcnt(4)
	v_mfma_f32_32x32x16_bf16 v[68:83], v[100:103], v[162:165], v[236:251]
	v_mfma_f32_32x32x16_bf16 v[100:115], v[84:87], v[162:165], v[236:251]
	ds_read_b128 v[84:87], v226 offset:36864
	v_permlane32_swap_b32_e32 v92, v94
	v_permlane32_swap_b32_e32 v93, v95
	v_permlane32_swap_b32_e32 v96, v98
	v_permlane32_swap_b32_e32 v97, v99
	v_add_co_u32_e32 v132, vcc, 0x10341000, v148
	s_waitcnt lgkmcnt(3)
	v_mfma_f32_32x32x16_bf16 v[100:115], v[88:91], v[158:161], v[100:115]
	v_addc_co_u32_e32 v133, vcc, 0, v149, vcc
	v_add_co_u32_e32 v174, vcc, 0x10389000, v148
	v_mfma_f32_32x32x16_bf16 v[68:83], v[134:137], v[158:161], v[68:83]
	ds_read_b128 v[88:91], v226 offset:32768
	v_addc_co_u32_e32 v175, vcc, 0, v149, vcc
	v_add_co_u32_e32 v176, vcc, 0x10340000, v196
	s_waitcnt lgkmcnt(2)
	v_mfma_f32_32x32x16_bf16 v[100:115], v[138:141], v[154:157], v[100:115]
	v_addc_co_u32_e32 v177, vcc, 0, v197, vcc
	v_mfma_f32_32x32x16_bf16 v[68:83], v[142:145], v[154:157], v[68:83]
	ds_read_b64_tr_b16 v[134:135], v211 offset:0
	ds_read_b64_tr_b16 v[136:137], v211 offset:0x800
	ds_read_b64_tr_b16 v[138:139], v211 offset:0x200
	ds_read_b64_tr_b16 v[140:141], v211 offset:0xa00
	ds_read_b64_tr_b16 v[142:143], v211 offset:0x400
	ds_read_b64_tr_b16 v[144:145], v211 offset:0xc00
	ds_read_b64_tr_b16 v[146:147], v211 offset:0x600
	ds_read_b64_tr_b16 v[148:149], v211 offset:0xe00
	s_waitcnt lgkmcnt(8)
	v_mfma_f32_32x32x16_bf16 v[100:115], v[84:87], v[150:153], v[100:115]
	v_mfma_f32_32x32x16_bf16 v[68:83], v[88:91], v[150:153], v[68:83]
	s_cmp_ge_u32 s4, s28
	s_cbranch_scc1 .Lnold_h2
	global_load_dwordx4 v[166:169], v[132:133], off
	global_load_dwordx4 v[170:173], v[174:175], off
	global_load_dwordx4 v[174:177], v[176:177], off offset:2048
; #define SBAR() __builtin_amdgcn_sched_barrier(0)
; template <bool FIRST> __device__ __forceinline__ void partialSM(f32x16& p0, f32x16& p1, float& m_reg, float& alpha, f32x16& negm, float c_cur) {
;   float pmax = p0[0];
; #pragma unroll
;   for (int r = 1; r < 16; ++r) pmax = fmaxf(pmax, p0[r]);
; #pragma unroll
;   for (int r = 0; r < 16; ++r) pmax = fmaxf(pmax, p1[r]);
;   { auto rr = __builtin_amdgcn_permlane32_swap(__float_as_uint(pmax), __float_as_uint(pmax), false, false);
;     pmax = fmaxf(__uint_as_float(rr[0]), __uint_as_float(rr[1])); }
; template <int D0> __device__ __forceinline__ void pv_one(f32x16& od, int vb, bf16x8 pa0, bf16x8 pa1, bf16x8 pa2, bf16x8 pa3) {
;   const s16x4 l0 = tr_read<v_rd_off(D0, 0, 0)>(vb), h0 = tr_read<v_rd_off(D0, 0, 1)>(vb), l1 = tr_read<v_rd_off(D0, 1, 0)>(vb), h1 = tr_read<v_rd_off(D0, 1, 1)>(vb);
;   const s16x4 l2 = tr_read<v_rd_off(D0, 2, 0)>(vb), h2 = tr_read<v_rd_off(D0, 2, 1)>(vb), l3 = tr_read<v_rd_off(D0, 3, 0)>(vb), h3 = tr_read<v_rd_off(D0, 3, 1)>(vb);
;   asm volatile("s_waitcnt lgkmcnt(0)" ::: "memory"); SBAR();
;     ...
;   od = __builtin_amdgcn_mfma_f32_32x32x16_bf16(pa0, PK(l0, h0), od, 0, 0, 0);
;   od = __builtin_amdgcn_mfma_f32_32x32x16_bf16(pa1, PK(l1, h1), od, 0, 0, 0);
;   od = __builtin_amdgcn_mfma_f32_32x32x16_bf16(pa2, PK(l2, h2), od, 0, 0, 0);
;   od = __builtin_amdgcn_mfma_f32_32x32x16_bf16(pa3, PK(l3, h3), od, 0, 0, 0);
;     ...
; }
; __device__ __forceinline__ void pv_d0(f32x16* o, int vb, bf16x8 pa0, bf16x8 pa1, bf16x8 pa2, bf16x8 pa3) {
;   pv_one<0>(o[0], vb, pa0, pa1, pa2, pa3); pv_one<1>(o[1], vb, pa0, pa1, pa2, pa3); pv_one<2>(o[2], vb, pa0, pa1, pa2, pa3); pv_one<3>(o[3], vb, pa0, pa1, pa2, pa3);
.Lnold_h2:
	s_addk_i32 s19, 0xffa1
	s_waitcnt lgkmcnt(6)
	v_mfma_f32_32x32x16_bf16 v[50:65], v[92:95], v[134:137], v[50:65]
	ds_read_b64_tr_b16 v[134:135], v211 offset:0x1000
	ds_read_b64_tr_b16 v[136:137], v211 offset:0x1800
	v_exp_f32_e32 v84, v116
	v_exp_f32_e32 v85, v117
	v_add_f32_e32 v235, v84, v235
	s_waitcnt lgkmcnt(6)
	v_mfma_f32_32x32x16_bf16 v[34:49], v[92:95], v[138:141], v[34:49]
	ds_read_b64_tr_b16 v[138:139], v211 offset:0x1200
	ds_read_b64_tr_b16 v[140:141], v211 offset:0x1a00
	v_exp_f32_e32 v86, v118
	v_add_f32_e32 v235, v85, v235
	v_exp_f32_e32 v87, v119
	v_add_f32_e32 v235, v86, v235
	s_waitcnt lgkmcnt(6)
	v_mfma_f32_32x32x16_bf16 v[18:33], v[92:95], v[142:145], v[18:33]
	ds_read_b64_tr_b16 v[142:143], v211 offset:0x1400
	ds_read_b64_tr_b16 v[144:145], v211 offset:0x1c00
	v_exp_f32_e32 v88, v120
	v_add_f32_e32 v235, v87, v235
	v_exp_f32_e32 v89, v121
	v_add_f32_e32 v235, v88, v235
	s_waitcnt lgkmcnt(6)
	v_mfma_f32_32x32x16_bf16 v[2:17], v[92:95], v[146:149], v[2:17]
	ds_read_b64_tr_b16 v[146:147], v211 offset:0x1600
	ds_read_b64_tr_b16 v[148:149], v211 offset:0x1e00
	v_exp_f32_e32 v90, v122
	v_add_f32_e32 v235, v89, v235
	v_exp_f32_e32 v91, v123
	v_add_f32_e32 v235, v90, v235
	v_add_f32_e32 v235, v91, v235
	s_waitcnt lgkmcnt(6)
	v_mfma_f32_32x32x16_bf16 v[50:65], v[96:99], v[134:137], v[50:65]
	ds_read_b64_tr_b16 v[134:135], v211 offset:0x2000
	ds_read_b64_tr_b16 v[136:137], v211 offset:0x2800
	v_cvt_pk_bf16_f32 v116, v84, v85
	v_cvt_pk_bf16_f32 v117, v86, v87
	v_cvt_pk_bf16_f32 v118, v88, v89
	v_cvt_pk_bf16_f32 v119, v90, v91
	s_waitcnt lgkmcnt(6)
	v_mfma_f32_32x32x16_bf16 v[34:49], v[96:99], v[138:141], v[34:49]
	ds_read_b64_tr_b16 v[138:139], v211 offset:0x2200
	ds_read_b64_tr_b16 v[140:141], v211 offset:0x2a00
	v_exp_f32_e32 v84, v124
	v_exp_f32_e32 v85, v125
	v_permlane32_swap_b32_e32 v116, v118
	v_permlane32_swap_b32_e32 v117, v119
	s_waitcnt lgkmcnt(6)
	v_mfma_f32_32x32x16_bf16 v[18:33], v[96:99], v[142:145], v[18:33]
	ds_read_b64_tr_b16 v[142:143], v211 offset:0x2400
	ds_read_b64_tr_b16 v[144:145], v211 offset:0x2c00
	v_exp_f32_e32 v86, v126
	v_exp_f32_e32 v87, v127
	v_exp_f32_e32 v88, v128
	s_waitcnt lgkmcnt(6)
	v_mfma_f32_32x32x16_bf16 v[2:17], v[96:99], v[146:149], v[2:17]
	ds_read_b64_tr_b16 v[146:147], v211 offset:0x2600
	ds_read_b64_tr_b16 v[148:149], v211 offset:0x2e00
	v_exp_f32_e32 v89, v129
	v_exp_f32_e32 v90, v130
	v_exp_f32_e32 v91, v131
	s_waitcnt lgkmcnt(6)
	v_mfma_f32_32x32x16_bf16 v[50:65], v[116:119], v[134:137], v[50:65]
	ds_read_b64_tr_b16 v[134:135], v211 offset:0x3000
	ds_read_b64_tr_b16 v[136:137], v211 offset:0x3800
	v_add_f32_e32 v235, v84, v235
	v_add_f32_e32 v235, v85, v235
	v_add_f32_e32 v235, v86, v235
	v_add_f32_e32 v235, v87, v235
	s_waitcnt lgkmcnt(6)
	v_mfma_f32_32x32x16_bf16 v[34:49], v[116:119], v[138:141], v[34:49]
	ds_read_b64_tr_b16 v[138:139], v211 offset:0x3200
	ds_read_b64_tr_b16 v[140:141], v211 offset:0x3a00
	v_add_f32_e32 v235, v88, v235
	v_add_f32_e32 v235, v89, v235
	v_add_f32_e32 v235, v90, v235
	v_add_f32_e32 v235, v91, v235
	v_mov_b32_e32 v252, v235
	s_waitcnt lgkmcnt(6)
	v_mfma_f32_32x32x16_bf16 v[18:33], v[116:119], v[142:145], v[18:33]
	ds_read_b64_tr_b16 v[142:143], v211 offset:0x3400
	ds_read_b64_tr_b16 v[144:145], v211 offset:0x3c00
	v_cvt_pk_bf16_f32 v120, v84, v85
	v_cvt_pk_bf16_f32 v121, v86, v87
	v_cvt_pk_bf16_f32 v122, v88, v89
	v_cvt_pk_bf16_f32 v123, v90, v91
	v_permlane32_swap_b32_e32 v235, v252
	s_waitcnt lgkmcnt(6)
	v_mfma_f32_32x32x16_bf16 v[2:17], v[116:119], v[146:149], v[2:17]
	ds_read_b64_tr_b16 v[146:147], v211 offset:0x3600
	ds_read_b64_tr_b16 v[148:149], v211 offset:0x3e00
	v_permlane32_swap_b32_e32 v120, v122
	v_permlane32_swap_b32_e32 v121, v123
	v_max_f32_e32 v132, v68, v69
	v_max3_f32 v132, v132, v70, v71
	v_max3_f32 v132, v132, v72, v73
	s_waitcnt lgkmcnt(6)
	v_mfma_f32_32x32x16_bf16 v[50:65], v[120:123], v[134:137], v[50:65]
	v_max3_f32 v132, v132, v74, v75
	v_max3_f32 v132, v132, v76, v77
	v_max3_f32 v132, v132, v78, v79
	v_max3_f32 v132, v132, v80, v81
	v_max3_f32 v132, v132, v82, v83
	s_waitcnt lgkmcnt(4)
	v_mfma_f32_32x32x16_bf16 v[34:49], v[120:123], v[138:141], v[34:49]
	v_max3_f32 v132, v132, v100, v101
	v_max3_f32 v132, v132, v102, v103
	v_max3_f32 v132, v132, v104, v105
	v_max3_f32 v132, v132, v106, v107
	v_max3_f32 v132, v132, v108, v109
	s_waitcnt lgkmcnt(2)
	v_mfma_f32_32x32x16_bf16 v[18:33], v[120:123], v[142:145], v[18:33]
	v_max3_f32 v132, v132, v110, v111
	v_max3_f32 v132, v132, v112, v113
	v_max3_f32 v132, v132, v114, v115
	v_mov_b32_e32 v133, v132
	s_waitcnt lgkmcnt(0)
	v_mfma_f32_32x32x16_bf16 v[2:17], v[120:123], v[146:149], v[2:17]
	v_permlane32_swap_b32_e32 v132, v133
	v_max_f32_e32 v196, v132, v133
	s_branch .Ljoin_h2

; #define SBAR() __builtin_amdgcn_sched_barrier(0)
; #define NEGM(t) do { if (BIAS) { const float c_ = cinit<BIAS, VIRT>((t), qw0, lut); if (c_ != c_cur) { c_cur = c_; const float nm_ = c_ - m_reg; _Pragma("unroll") for (int r = 0; r < 16; ++r) negm[r] = nm_; } } } while (0)
; template <int DQK, bool BIAS, bool VIRT = false>
; __device__ __forceinline__ void attn_pass(const bf16_t* __restrict__ Qb, const bf16_t* __restrict__ Kh, const bf16_t* __restrict__ Vh, int L, int NT, int qw0, const float* lut, f32x16 (&o)[4], char* lds, int nact) {
;     ...
;     NEGM(j + 1); SBAR(); qkt<DQK>(pA0, pA1, K_lds, qr, r32, hi, negm);
;     finishSM(pB0, pB1, alB, l_reg, pa0, pa1, pa2, pa3); SBAR();
.Lold_h2:
	v_mov_b64_e32 v[100:101], v[116:117]
	v_mov_b64_e32 v[102:103], v[118:119]
	v_mov_b64_e32 v[104:105], v[120:121]
	v_mov_b64_e32 v[106:107], v[122:123]
	v_mov_b64_e32 v[108:109], v[124:125]
	v_mov_b64_e32 v[110:111], v[126:127]
	v_mov_b64_e32 v[112:113], v[128:129]
	v_mov_b64_e32 v[114:115], v[130:131]
	s_waitcnt lgkmcnt(0)
	v_cmp_neq_f32_e32 vcc, v133, v66
	s_add_i32 s4, s25, -1
	s_cbranch_vccnz .Lcupd_h2

; template <bool FIRST> __device__ __forceinline__ void partialSM(f32x16& p0, f32x16& p1, float& m_reg, float& alpha, f32x16& negm, float c_cur) {
;   float pmax = p0[0];
; #pragma unroll
;   for (int r = 1; r < 16; ++r) pmax = fmaxf(pmax, p0[r]);
; #pragma unroll
;   for (int r = 0; r < 16; ++r) pmax = fmaxf(pmax, p1[r]);
;   { auto rr = __builtin_amdgcn_permlane32_swap(__float_as_uint(pmax), __float_as_uint(pmax), false, false);
;     pmax = fmaxf(__uint_as_float(rr[0]), __uint_as_float(rr[1])); }
.LBB0_240:
	v_max_f32_e32 v100, v69, v69
	v_max_f32_e32 v101, v68, v68
	v_max_f32_e32 v100, v101, v100
	v_max3_f32 v100, v100, v70, v71
	v_max3_f32 v100, v100, v72, v73
	v_max3_f32 v100, v100, v74, v75
	v_max3_f32 v100, v100, v76, v77
	v_max3_f32 v100, v100, v78, v79
	v_max3_f32 v100, v100, v80, v81
	v_max3_f32 v100, v100, v82, v83
	v_max3_f32 v100, v100, v116, v117
	v_max3_f32 v100, v100, v118, v119
	v_max3_f32 v100, v100, v120, v121
	v_max3_f32 v100, v100, v122, v123
	v_max3_f32 v100, v100, v124, v125
	v_max3_f32 v100, v100, v126, v127
	v_max3_f32 v100, v100, v128, v129
	v_max3_f32 v100, v100, v130, v131
	v_mov_b32_e32 v101, v100
	s_nop 1
	v_permlane32_swap_b32_e32 v100, v101
	v_max_f32_e32 v101, v101, v101
	v_max_f32_e32 v100, v100, v100
	v_max_f32_e32 v196, v100, v101
	v_mov_b64_e32 v[100:101], v[116:117]
	v_mov_b64_e32 v[102:103], v[118:119]
	v_mov_b64_e32 v[104:105], v[120:121]
	v_mov_b64_e32 v[106:107], v[122:123]
	v_mov_b64_e32 v[108:109], v[124:125]
	v_mov_b64_e32 v[110:111], v[126:127]
	v_mov_b64_e32 v[112:113], v[128:129]
	v_mov_b64_e32 v[114:115], v[130:131]

; template <bool FIRST> __device__ __forceinline__ void partialSM(f32x16& p0, f32x16& p1, float& m_reg, float& alpha, f32x16& negm, float c_cur) {
;     ...
;   alpha = 1.f;
.LBB0_241:
	v_mov_b32_e32 v133, 1.0
	v_mov_b32_e32 v233, v234

; template <bool FIRST> __device__ __forceinline__ void partialSM(f32x16& p0, f32x16& p1, float& m_reg, float& alpha, f32x16& negm, float c_cur) {
;     ...
;   if (FIRST || !__builtin_expect(__all(pmax <= THR2), 1)) {
;     const float d = FIRST ? pmax : fmaxf(pmax, 0.f); m_reg += d; if (!FIRST) alpha = __builtin_amdgcn_exp2f(-d);
; #pragma unroll
;     for (int r = 0; r < 16; ++r) { p0[r] -= d; p1[r] -= d; }
;     const float nm = c_cur - m_reg;
; #pragma unroll
;     for (int r = 0; r < 16; ++r) negm[r] = nm;
;   }
.LBB0_255:
	v_max_f32_e32 v69, v100, v100
	v_max_f32_e32 v100, 0, v69
	v_add_f32_e32 v234, v233, v100
	v_sub_f32_e32 v132, v66, v234
	v_exp_f32_e64 v232, -v100
	v_pk_add_f32 v[84:85], v[84:85], v[100:101] op_sel_hi:[1,0] neg_lo:[0,1] neg_hi:[0,1]
	v_pk_add_f32 v[86:87], v[86:87], v[100:101] op_sel_hi:[1,0] neg_lo:[0,1] neg_hi:[0,1]
	v_pk_add_f32 v[88:89], v[88:89], v[100:101] op_sel_hi:[1,0] neg_lo:[0,1] neg_hi:[0,1]
	v_pk_add_f32 v[90:91], v[90:91], v[100:101] op_sel_hi:[1,0] neg_lo:[0,1] neg_hi:[0,1]
	v_pk_add_f32 v[92:93], v[92:93], v[100:101] op_sel_hi:[1,0] neg_lo:[0,1] neg_hi:[0,1]
	v_pk_add_f32 v[94:95], v[94:95], v[100:101] op_sel_hi:[1,0] neg_lo:[0,1] neg_hi:[0,1]
	v_pk_add_f32 v[96:97], v[96:97], v[100:101] op_sel_hi:[1,0] neg_lo:[0,1] neg_hi:[0,1]
	v_pk_add_f32 v[98:99], v[98:99], v[100:101] op_sel_hi:[1,0] neg_lo:[0,1] neg_hi:[0,1]
	v_sub_f32_e32 v131, v131, v100
	v_sub_f32_e32 v130, v130, v100
	v_sub_f32_e32 v129, v129, v100
	v_sub_f32_e32 v128, v128, v100
	v_sub_f32_e32 v127, v127, v100
	v_sub_f32_e32 v126, v126, v100
	v_sub_f32_e32 v125, v125, v100
	v_sub_f32_e32 v124, v124, v100
	v_sub_f32_e32 v123, v123, v100
	v_sub_f32_e32 v122, v122, v100
	v_sub_f32_e32 v121, v121, v100
	v_sub_f32_e32 v120, v120, v100
	v_sub_f32_e32 v119, v119, v100
	v_sub_f32_e32 v118, v118, v100
	v_sub_f32_e32 v117, v117, v100
	v_sub_f32_e32 v116, v116, v100
	v_mov_b32_e32 v236, v132
	v_mov_b32_e32 v237, v132
	v_mov_b32_e32 v238, v132
	v_mov_b32_e32 v239, v132
	v_mov_b32_e32 v240, v132
	v_mov_b32_e32 v241, v132
	v_mov_b32_e32 v242, v132
	v_mov_b32_e32 v243, v132
	v_mov_b32_e32 v244, v132
	v_mov_b32_e32 v245, v132
	v_mov_b32_e32 v246, v132
	v_mov_b32_e32 v247, v132
	v_mov_b32_e32 v248, v132
	v_mov_b32_e32 v249, v132
	v_mov_b32_e32 v250, v132
	v_mov_b32_e32 v251, v132
	s_branch .LBB0_225

; template <bool FIRST> __device__ __forceinline__ void partialSM(f32x16& p0, f32x16& p1, float& m_reg, float& alpha, f32x16& negm, float c_cur) {
;     ...
;   if (FIRST || !__builtin_expect(__all(pmax <= THR2), 1)) {
;     const float d = FIRST ? pmax : fmaxf(pmax, 0.f); m_reg += d; if (!FIRST) alpha = __builtin_amdgcn_exp2f(-d);
; #pragma unroll
;     for (int r = 0; r < 16; ++r) { p0[r] -= d; p1[r] -= d; }
;     const float nm = c_cur - m_reg;
; #pragma unroll
;     for (int r = 0; r < 16; ++r) negm[r] = nm;
;   }
.LBB0_259:
	v_max_f32_e32 v196, v196, v196
	v_max_f32_e32 v196, 0, v196
	v_exp_f32_e64 v133, -v196
	v_add_f32_e32 v233, v234, v196
	v_sub_f32_e32 v132, v66, v233
	v_pk_add_f32 v[68:69], v[68:69], v[196:197] op_sel_hi:[1,0] neg_lo:[0,1] neg_hi:[0,1]
	v_pk_add_f32 v[70:71], v[70:71], v[196:197] op_sel_hi:[1,0] neg_lo:[0,1] neg_hi:[0,1]
	v_pk_add_f32 v[72:73], v[72:73], v[196:197] op_sel_hi:[1,0] neg_lo:[0,1] neg_hi:[0,1]
	v_pk_add_f32 v[74:75], v[74:75], v[196:197] op_sel_hi:[1,0] neg_lo:[0,1] neg_hi:[0,1]
	v_pk_add_f32 v[76:77], v[76:77], v[196:197] op_sel_hi:[1,0] neg_lo:[0,1] neg_hi:[0,1]
	v_pk_add_f32 v[78:79], v[78:79], v[196:197] op_sel_hi:[1,0] neg_lo:[0,1] neg_hi:[0,1]
	v_pk_add_f32 v[80:81], v[80:81], v[196:197] op_sel_hi:[1,0] neg_lo:[0,1] neg_hi:[0,1]
	v_pk_add_f32 v[82:83], v[82:83], v[196:197] op_sel_hi:[1,0] neg_lo:[0,1] neg_hi:[0,1]
	v_sub_f32_e32 v115, v115, v196
	v_sub_f32_e32 v114, v114, v196
	v_sub_f32_e32 v113, v113, v196
	v_sub_f32_e32 v112, v112, v196
	v_sub_f32_e32 v111, v111, v196
	v_sub_f32_e32 v110, v110, v196
	v_sub_f32_e32 v109, v109, v196
	v_sub_f32_e32 v108, v108, v196
	v_sub_f32_e32 v107, v107, v196
	v_sub_f32_e32 v106, v106, v196
	v_sub_f32_e32 v105, v105, v196
	v_sub_f32_e32 v104, v104, v196
	v_sub_f32_e32 v103, v103, v196
	v_sub_f32_e32 v102, v102, v196
	v_sub_f32_e32 v101, v101, v196
	v_sub_f32_e32 v100, v100, v196
	v_mov_b32_e32 v236, v132
	v_mov_b32_e32 v237, v132
	v_mov_b32_e32 v238, v132
	v_mov_b32_e32 v239, v132
	v_mov_b32_e32 v240, v132
	v_mov_b32_e32 v241, v132
	v_mov_b32_e32 v242, v132
	v_mov_b32_e32 v243, v132
	v_mov_b32_e32 v244, v132
	v_mov_b32_e32 v245, v132
	v_mov_b32_e32 v246, v132
	v_mov_b32_e32 v247, v132
	v_mov_b32_e32 v248, v132
	v_mov_b32_e32 v249, v132
	v_mov_b32_e32 v250, v132
	v_mov_b32_e32 v251, v132
	s_branch .LBB0_243
